# as v5 with nt cache policy on the read-once f32 weight loads of the conversion loops
# speedup vs baseline: 1.0114x; 1.0037x over previous
.LBB0_15:
	s_mul_hi_i32 s4, s12, 0x2fa0be83
	s_lshr_b32 s5, s4, 31
	s_ashr_i32 s4, s4, 6
	s_add_i32 s5, s4, s5
	s_mul_i32 s4, s5, 0xffffaa00
	s_add_i32 s6, s13, s4
	s_lshl_b32 s4, s5, 6
	v_or_b32_e32 v70, s4, v1
	s_ashr_i32 s7, s6, 31
	v_lshl_add_u64 v[6:7], s[6:7], 2, v[66:67]
	v_or_b32_e32 v4, 4, v70
	v_mad_i64_i32 v[2:3], s[16:17], v70, s15, v[6:7]
	v_mad_i64_i32 v[4:5], s[16:17], v4, s15, v[6:7]
	global_load_dwordx4 v[50:53], v[2:3], off nt
	global_load_dwordx4 v[34:37], v[4:5], off nt
	v_or_b32_e32 v2, 8, v70
	v_or_b32_e32 v4, 12, v70
	v_mad_i64_i32 v[2:3], s[16:17], v2, s15, v[6:7]
	v_mad_i64_i32 v[4:5], s[16:17], v4, s15, v[6:7]
	global_load_dwordx4 v[42:45], v[2:3], off nt
	global_load_dwordx4 v[22:25], v[4:5], off nt
	v_or_b32_e32 v2, 16, v70
	v_or_b32_e32 v4, 20, v70
	v_mad_i64_i32 v[2:3], s[16:17], v2, s15, v[6:7]
	v_mad_i64_i32 v[4:5], s[16:17], v4, s15, v[6:7]
	global_load_dwordx4 v[38:41], v[2:3], off nt
	global_load_dwordx4 v[14:17], v[4:5], off nt
	v_or_b32_e32 v2, 24, v70
	v_or_b32_e32 v4, 28, v70
	v_mad_i64_i32 v[2:3], s[16:17], v2, s15, v[6:7]
	v_mad_i64_i32 v[4:5], s[16:17], v4, s15, v[6:7]
	v_or_b32_e32 v48, 56, v70
	global_load_dwordx4 v[30:33], v[2:3], off nt
	global_load_dwordx4 v[10:13], v[4:5], off nt
	v_or_b32_e32 v2, 32, v70
	v_or_b32_e32 v4, 36, v70
	v_or_b32_e32 v8, 40, v70
	v_or_b32_e32 v26, 44, v70
	v_or_b32_e32 v28, 48, v70
	v_or_b32_e32 v46, 52, v70
	v_mad_i64_i32 v[82:83], s[16:17], v48, s15, v[6:7]
	v_or_b32_e32 v48, 60, v70
	v_mad_i64_i32 v[2:3], s[16:17], v2, s15, v[6:7]
	v_mad_i64_i32 v[4:5], s[16:17], v4, s15, v[6:7]
	v_mad_i64_i32 v[8:9], s[16:17], v8, s15, v[6:7]
	v_mad_i64_i32 v[26:27], s[16:17], v26, s15, v[6:7]
	v_mad_i64_i32 v[28:29], s[16:17], v28, s15, v[6:7]
	v_mad_i64_i32 v[46:47], s[16:17], v46, s15, v[6:7]
	v_mad_i64_i32 v[6:7], s[16:17], v48, s15, v[6:7]
	global_load_dwordx4 v[18:21], v[2:3], off nt
	s_nop 0
	global_load_dwordx4 v[2:5], v[4:5], off nt
	s_nop 0
	global_load_dwordx4 v[62:65], v[8:9], off nt
	global_load_dwordx4 v[58:61], v[26:27], off nt
	global_load_dwordx4 v[54:57], v[28:29], off nt
	s_nop 0
	global_load_dwordx4 v[46:49], v[46:47], off nt
	s_nop 0
	global_load_dwordx4 v[26:29], v[82:83], off nt
	s_nop 0
	global_load_dwordx4 v[6:9], v[6:7], off nt
	s_and_b64 vcc, exec, s[2:3]
	s_cbranch_vccnz .LBB0_14
	v_ashrrev_i32_e32 v71, 31, v70
	v_lshl_add_u64 v[70:71], v[70:71], 2, s[60:61]
	global_load_dword v82, v[70:71], off
	global_load_dword v84, v[70:71], off offset:16
	global_load_dword v86, v[70:71], off offset:32
	global_load_dword v88, v[70:71], off offset:48
	global_load_dword v90, v[70:71], off offset:64
	global_load_dword v92, v[70:71], off offset:80
	global_load_dword v94, v[70:71], off offset:96
	global_load_dword v96, v[70:71], off offset:112
	global_load_dword v98, v[70:71], off offset:128
	global_load_dword v100, v[70:71], off offset:144
	global_load_dword v102, v[70:71], off offset:160
	global_load_dword v104, v[70:71], off offset:176
	global_load_dword v106, v[70:71], off offset:192
	global_load_dword v108, v[70:71], off offset:208
	global_load_dword v110, v[70:71], off offset:224
	s_nop 0
	global_load_dword v70, v[70:71], off offset:240
	s_waitcnt vmcnt(15)
	v_pk_mul_f32 v[52:53], v[52:53], v[82:83] op_sel_hi:[1,0]
	v_pk_mul_f32 v[50:51], v[50:51], v[82:83] op_sel_hi:[1,0]
	s_waitcnt vmcnt(14)
	v_pk_mul_f32 v[36:37], v[36:37], v[84:85] op_sel_hi:[1,0]
	v_pk_mul_f32 v[34:35], v[34:35], v[84:85] op_sel_hi:[1,0]
	s_waitcnt vmcnt(13)
	v_pk_mul_f32 v[44:45], v[44:45], v[86:87] op_sel_hi:[1,0]
	v_pk_mul_f32 v[42:43], v[42:43], v[86:87] op_sel_hi:[1,0]
	s_waitcnt vmcnt(12)
	v_pk_mul_f32 v[24:25], v[24:25], v[88:89] op_sel_hi:[1,0]
	v_pk_mul_f32 v[22:23], v[22:23], v[88:89] op_sel_hi:[1,0]
	s_waitcnt vmcnt(11)
	v_pk_mul_f32 v[40:41], v[40:41], v[90:91] op_sel_hi:[1,0]
	v_pk_mul_f32 v[38:39], v[38:39], v[90:91] op_sel_hi:[1,0]
	s_waitcnt vmcnt(10)
	v_pk_mul_f32 v[16:17], v[16:17], v[92:93] op_sel_hi:[1,0]
	v_pk_mul_f32 v[14:15], v[14:15], v[92:93] op_sel_hi:[1,0]
	s_waitcnt vmcnt(9)
	v_pk_mul_f32 v[32:33], v[32:33], v[94:95] op_sel_hi:[1,0]
	v_pk_mul_f32 v[30:31], v[30:31], v[94:95] op_sel_hi:[1,0]
	s_waitcnt vmcnt(8)
	v_pk_mul_f32 v[12:13], v[12:13], v[96:97] op_sel_hi:[1,0]
	v_pk_mul_f32 v[10:11], v[10:11], v[96:97] op_sel_hi:[1,0]
	s_waitcnt vmcnt(7)
	v_pk_mul_f32 v[20:21], v[20:21], v[98:99] op_sel_hi:[1,0]
	v_pk_mul_f32 v[18:19], v[18:19], v[98:99] op_sel_hi:[1,0]
	s_waitcnt vmcnt(6)
	v_pk_mul_f32 v[4:5], v[4:5], v[100:101] op_sel_hi:[1,0]
	v_pk_mul_f32 v[2:3], v[2:3], v[100:101] op_sel_hi:[1,0]
	s_waitcnt vmcnt(5)
	v_pk_mul_f32 v[64:65], v[64:65], v[102:103] op_sel_hi:[1,0]
	v_pk_mul_f32 v[62:63], v[62:63], v[102:103] op_sel_hi:[1,0]
	s_waitcnt vmcnt(4)
	v_pk_mul_f32 v[60:61], v[60:61], v[104:105] op_sel_hi:[1,0]
	v_pk_mul_f32 v[58:59], v[58:59], v[104:105] op_sel_hi:[1,0]
	s_waitcnt vmcnt(3)
	v_pk_mul_f32 v[56:57], v[56:57], v[106:107] op_sel_hi:[1,0]
	v_pk_mul_f32 v[54:55], v[54:55], v[106:107] op_sel_hi:[1,0]
	s_waitcnt vmcnt(2)
	v_pk_mul_f32 v[48:49], v[48:49], v[108:109] op_sel_hi:[1,0]
	v_pk_mul_f32 v[46:47], v[46:47], v[108:109] op_sel_hi:[1,0]
	s_waitcnt vmcnt(1)
	v_pk_mul_f32 v[28:29], v[28:29], v[110:111] op_sel_hi:[1,0]
	v_pk_mul_f32 v[26:27], v[26:27], v[110:111] op_sel_hi:[1,0]
	s_waitcnt vmcnt(0)
	v_pk_mul_f32 v[8:9], v[8:9], v[70:71] op_sel_hi:[1,0]
	v_pk_mul_f32 v[6:7], v[6:7], v[70:71] op_sel_hi:[1,0]
	s_branch .LBB0_14

.LBB0_20:
	s_ashr_i32 s4, s6, 31
	s_lshr_b32 s4, s4, 27
	s_add_i32 s4, s6, s4
	s_ashr_i32 s4, s4, 5
	s_lshl_b32 s5, s4, 11
	s_lshl_b32 s4, s4, 6
	v_or_b32_e32 v70, s4, v1
	s_sub_i32 s10, s7, s5
	v_or_b32_e32 v4, 4, v70
	v_or_b32_e32 v10, 8, v70
	v_or_b32_e32 v12, 12, v70
	v_or_b32_e32 v18, 16, v70
	v_or_b32_e32 v20, 20, v70
	v_or_b32_e32 v26, 24, v70
	v_or_b32_e32 v28, 28, v70
	v_or_b32_e32 v34, 32, v70
	v_or_b32_e32 v36, 36, v70
	v_or_b32_e32 v42, 40, v70
	v_or_b32_e32 v44, 44, v70
	v_or_b32_e32 v50, 48, v70
	v_or_b32_e32 v52, 52, v70
	v_or_b32_e32 v60, 56, v70
	v_or_b32_e32 v62, 60, v70
	s_ashr_i32 s11, s10, 31
	v_ashrrev_i32_e32 v71, 31, v70
	v_ashrrev_i32_e32 v5, 31, v4
	v_ashrrev_i32_e32 v11, 31, v10
	v_ashrrev_i32_e32 v13, 31, v12
	v_ashrrev_i32_e32 v19, 31, v18
	v_ashrrev_i32_e32 v21, 31, v20
	v_ashrrev_i32_e32 v27, 31, v26
	v_ashrrev_i32_e32 v29, 31, v28
	v_ashrrev_i32_e32 v35, 31, v34
	v_ashrrev_i32_e32 v37, 31, v36
	v_ashrrev_i32_e32 v43, 31, v42
	v_ashrrev_i32_e32 v45, 31, v44
	v_ashrrev_i32_e32 v51, 31, v50
	v_ashrrev_i32_e32 v53, 31, v52
	v_ashrrev_i32_e32 v61, 31, v60
	v_ashrrev_i32_e32 v63, 31, v62
	v_lshl_add_u64 v[58:59], s[10:11], 2, v[66:67]
	v_lshlrev_b64 v[2:3], 13, v[70:71]
	v_lshlrev_b64 v[4:5], 13, v[4:5]
	v_lshlrev_b64 v[10:11], 13, v[10:11]
	v_lshlrev_b64 v[12:13], 13, v[12:13]
	v_lshlrev_b64 v[18:19], 13, v[18:19]
	v_lshlrev_b64 v[20:21], 13, v[20:21]
	v_lshlrev_b64 v[26:27], 13, v[26:27]
	v_lshlrev_b64 v[28:29], 13, v[28:29]
	v_lshlrev_b64 v[34:35], 13, v[34:35]
	v_lshlrev_b64 v[36:37], 13, v[36:37]
	v_lshlrev_b64 v[42:43], 13, v[42:43]
	v_lshlrev_b64 v[44:45], 13, v[44:45]
	v_lshlrev_b64 v[50:51], 13, v[50:51]
	v_lshlrev_b64 v[52:53], 13, v[52:53]
	v_lshlrev_b64 v[60:61], 13, v[60:61]
	v_lshlrev_b64 v[62:63], 13, v[62:63]
	v_lshl_add_u64 v[2:3], v[58:59], 0, v[2:3]
	v_lshl_add_u64 v[4:5], v[58:59], 0, v[4:5]
	v_lshl_add_u64 v[10:11], v[58:59], 0, v[10:11]
	v_lshl_add_u64 v[12:13], v[58:59], 0, v[12:13]
	v_lshl_add_u64 v[18:19], v[58:59], 0, v[18:19]
	v_lshl_add_u64 v[20:21], v[58:59], 0, v[20:21]
	v_lshl_add_u64 v[26:27], v[58:59], 0, v[26:27]
	v_lshl_add_u64 v[28:29], v[58:59], 0, v[28:29]
	v_lshl_add_u64 v[34:35], v[58:59], 0, v[34:35]
	v_lshl_add_u64 v[36:37], v[58:59], 0, v[36:37]
	v_lshl_add_u64 v[42:43], v[58:59], 0, v[42:43]
	v_lshl_add_u64 v[44:45], v[58:59], 0, v[44:45]
	v_lshl_add_u64 v[50:51], v[58:59], 0, v[50:51]
	v_lshl_add_u64 v[52:53], v[58:59], 0, v[52:53]
	v_lshl_add_u64 v[60:61], v[58:59], 0, v[60:61]
	v_lshl_add_u64 v[58:59], v[58:59], 0, v[62:63]
	global_load_dwordx4 v[6:9], v[2:3], off nt
	s_nop 0
	global_load_dwordx4 v[2:5], v[4:5], off nt
	s_nop 0
	global_load_dwordx4 v[14:17], v[10:11], off nt
	s_nop 0
	global_load_dwordx4 v[10:13], v[12:13], off nt
	s_nop 0
	global_load_dwordx4 v[22:25], v[18:19], off nt
	s_nop 0
	global_load_dwordx4 v[18:21], v[20:21], off nt
	s_nop 0
	global_load_dwordx4 v[30:33], v[26:27], off nt
	s_nop 0
	global_load_dwordx4 v[26:29], v[28:29], off nt
	s_nop 0
	global_load_dwordx4 v[38:41], v[34:35], off nt
	s_nop 0
	global_load_dwordx4 v[34:37], v[36:37], off nt
	s_nop 0
	global_load_dwordx4 v[46:49], v[42:43], off nt
	s_nop 0
	global_load_dwordx4 v[42:45], v[44:45], off nt
	s_nop 0
	global_load_dwordx4 v[54:57], v[50:51], off nt
	s_nop 0
	global_load_dwordx4 v[50:53], v[52:53], off nt
	s_nop 0
	global_load_dwordx4 v[62:65], v[60:61], off nt
	s_nop 0
	global_load_dwordx4 v[58:61], v[58:59], off nt
	s_and_b64 vcc, exec, s[2:3]
	s_sub_i32 s9, 0, s5
	s_cbranch_vccnz .LBB0_19
	v_readlane_b32 s12, v254, 44
	v_readlane_b32 s14, v254, 46
	v_readlane_b32 s15, v254, 47
	v_readlane_b32 s13, v254, 45
	v_readlane_b32 s16, v254, 48
	v_lshl_add_u64 v[70:71], v[70:71], 2, s[14:15]
	global_load_dword v76, v[70:71], off
	global_load_dword v78, v[70:71], off offset:16
	global_load_dword v80, v[70:71], off offset:32
	global_load_dword v82, v[70:71], off offset:48
	global_load_dword v84, v[70:71], off offset:64
	global_load_dword v86, v[70:71], off offset:80
	global_load_dword v88, v[70:71], off offset:96
	global_load_dword v90, v[70:71], off offset:112
	global_load_dword v92, v[70:71], off offset:128
	global_load_dword v94, v[70:71], off offset:144
	global_load_dword v96, v[70:71], off offset:160
	global_load_dword v98, v[70:71], off offset:176
	global_load_dword v100, v[70:71], off offset:192
	global_load_dword v102, v[70:71], off offset:208
	global_load_dword v104, v[70:71], off offset:224
	s_nop 0
	global_load_dword v70, v[70:71], off offset:240
	v_readlane_b32 s17, v254, 49
	v_readlane_b32 s18, v254, 50
	v_readlane_b32 s19, v254, 51
	v_readlane_b32 s20, v254, 52
	v_readlane_b32 s21, v254, 53
	v_readlane_b32 s22, v254, 54
	v_readlane_b32 s23, v254, 55
	v_readlane_b32 s24, v254, 56
	v_readlane_b32 s25, v254, 57
	v_readlane_b32 s26, v254, 58
	v_readlane_b32 s27, v254, 59
	s_waitcnt vmcnt(15)
	v_pk_mul_f32 v[8:9], v[8:9], v[76:77] op_sel_hi:[1,0]
	v_pk_mul_f32 v[6:7], v[6:7], v[76:77] op_sel_hi:[1,0]
	s_waitcnt vmcnt(14)
	v_pk_mul_f32 v[4:5], v[4:5], v[78:79] op_sel_hi:[1,0]
	v_pk_mul_f32 v[2:3], v[2:3], v[78:79] op_sel_hi:[1,0]
	s_waitcnt vmcnt(13)
	v_pk_mul_f32 v[16:17], v[16:17], v[80:81] op_sel_hi:[1,0]
	v_pk_mul_f32 v[14:15], v[14:15], v[80:81] op_sel_hi:[1,0]
	s_waitcnt vmcnt(12)
	v_pk_mul_f32 v[12:13], v[12:13], v[82:83] op_sel_hi:[1,0]
	v_pk_mul_f32 v[10:11], v[10:11], v[82:83] op_sel_hi:[1,0]
	s_waitcnt vmcnt(11)
	v_pk_mul_f32 v[24:25], v[24:25], v[84:85] op_sel_hi:[1,0]
	v_pk_mul_f32 v[22:23], v[22:23], v[84:85] op_sel_hi:[1,0]
	s_waitcnt vmcnt(10)
	v_pk_mul_f32 v[20:21], v[20:21], v[86:87] op_sel_hi:[1,0]
	v_pk_mul_f32 v[18:19], v[18:19], v[86:87] op_sel_hi:[1,0]
	s_waitcnt vmcnt(9)
	v_pk_mul_f32 v[32:33], v[32:33], v[88:89] op_sel_hi:[1,0]
	v_pk_mul_f32 v[30:31], v[30:31], v[88:89] op_sel_hi:[1,0]
	s_waitcnt vmcnt(8)
	v_pk_mul_f32 v[28:29], v[28:29], v[90:91] op_sel_hi:[1,0]
	v_pk_mul_f32 v[26:27], v[26:27], v[90:91] op_sel_hi:[1,0]
	s_waitcnt vmcnt(7)
	v_pk_mul_f32 v[40:41], v[40:41], v[92:93] op_sel_hi:[1,0]
	v_pk_mul_f32 v[38:39], v[38:39], v[92:93] op_sel_hi:[1,0]
	s_waitcnt vmcnt(6)
	v_pk_mul_f32 v[36:37], v[36:37], v[94:95] op_sel_hi:[1,0]
	v_pk_mul_f32 v[34:35], v[34:35], v[94:95] op_sel_hi:[1,0]
	s_waitcnt vmcnt(5)
	v_pk_mul_f32 v[48:49], v[48:49], v[96:97] op_sel_hi:[1,0]
	v_pk_mul_f32 v[46:47], v[46:47], v[96:97] op_sel_hi:[1,0]
	s_waitcnt vmcnt(4)
	v_pk_mul_f32 v[44:45], v[44:45], v[98:99] op_sel_hi:[1,0]
	v_pk_mul_f32 v[42:43], v[42:43], v[98:99] op_sel_hi:[1,0]
	s_waitcnt vmcnt(3)
	v_pk_mul_f32 v[56:57], v[56:57], v[100:101] op_sel_hi:[1,0]
	v_pk_mul_f32 v[54:55], v[54:55], v[100:101] op_sel_hi:[1,0]
	s_waitcnt vmcnt(2)
	v_pk_mul_f32 v[52:53], v[52:53], v[102:103] op_sel_hi:[1,0]
	v_pk_mul_f32 v[50:51], v[50:51], v[102:103] op_sel_hi:[1,0]
	s_waitcnt vmcnt(1)
	v_pk_mul_f32 v[64:65], v[64:65], v[104:105] op_sel_hi:[1,0]
	v_pk_mul_f32 v[62:63], v[62:63], v[104:105] op_sel_hi:[1,0]
	s_waitcnt vmcnt(0)
	v_pk_mul_f32 v[60:61], v[60:61], v[70:71] op_sel_hi:[1,0]
	v_pk_mul_f32 v[58:59], v[58:59], v[70:71] op_sel_hi:[1,0]
	s_branch .LBB0_19

.LBB0_306:
	s_ashr_i32 s7, s1, 31
	s_lshr_b32 s7, s7, 26
	s_add_i32 s7, s1, s7
	s_ashr_i32 s10, s7, 6
	s_and_b32 s8, s7, 0xffffffc0
	s_lshl_b32 s7, s10, 12
	v_or_b32_e32 v40, s8, v1
	s_mul_i32 s11, s10, 0xfd500000
	s_sub_i32 s10, s3, s7
	v_or_b32_e32 v42, 4, v40
	v_or_b32_e32 v44, 8, v40
	v_or_b32_e32 v46, 12, v40
	v_or_b32_e32 v48, 16, v40
	v_or_b32_e32 v50, 20, v40
	v_or_b32_e32 v52, 24, v40
	v_or_b32_e32 v54, 28, v40
	s_ashr_i32 s9, s8, 31
	v_ashrrev_i32_e32 v41, 31, v40
	v_or_b32_e32 v56, 32, v40
	v_or_b32_e32 v58, 36, v40
	v_or_b32_e32 v60, 40, v40
	v_or_b32_e32 v62, 44, v40
	v_or_b32_e32 v64, 48, v40
	v_or_b32_e32 v66, 52, v40
	v_or_b32_e32 v68, 56, v40
	v_or_b32_e32 v70, 60, v40
	v_add_u32_e32 v74, s11, v7
	s_ashr_i32 s11, s10, 31
	v_ashrrev_i32_e32 v43, 31, v42
	v_ashrrev_i32_e32 v45, 31, v44
	v_ashrrev_i32_e32 v47, 31, v46
	v_ashrrev_i32_e32 v49, 31, v48
	v_ashrrev_i32_e32 v51, 31, v50
	v_ashrrev_i32_e32 v53, 31, v52
	v_ashrrev_i32_e32 v55, 31, v54
	v_lshl_add_u64 v[72:73], s[8:9], 1, v[4:5]
	v_lshlrev_b64 v[40:41], 14, v[40:41]
	v_ashrrev_i32_e32 v57, 31, v56
	v_ashrrev_i32_e32 v59, 31, v58
	v_ashrrev_i32_e32 v61, 31, v60
	v_ashrrev_i32_e32 v63, 31, v62
	v_ashrrev_i32_e32 v65, 31, v64
	v_ashrrev_i32_e32 v67, 31, v66
	v_ashrrev_i32_e32 v69, 31, v68
	v_ashrrev_i32_e32 v71, 31, v70
	v_ashrrev_i32_e32 v75, 31, v74
	v_add_u32_e32 v76, 0x15800, v74
	v_add_u32_e32 v78, 0x2b000, v74
	v_add_u32_e32 v80, 0x40800, v74
	v_add_u32_e32 v82, 0x56000, v74
	v_add_u32_e32 v84, 0x6b800, v74
	v_add_u32_e32 v86, 0x81000, v74
	v_add_u32_e32 v88, 0x96800, v74
	v_lshl_add_u64 v[90:91], s[10:11], 2, v[2:3]
	v_lshlrev_b64 v[42:43], 14, v[42:43]
	v_lshlrev_b64 v[44:45], 14, v[44:45]
	v_lshlrev_b64 v[46:47], 14, v[46:47]
	v_lshlrev_b64 v[48:49], 14, v[48:49]
	v_lshlrev_b64 v[50:51], 14, v[50:51]
	v_lshlrev_b64 v[52:53], 14, v[52:53]
	v_lshlrev_b64 v[54:55], 14, v[54:55]
	v_lshlrev_b64 v[56:57], 14, v[56:57]
	v_lshlrev_b64 v[58:59], 14, v[58:59]
	v_lshlrev_b64 v[60:61], 14, v[60:61]
	v_lshlrev_b64 v[62:63], 14, v[62:63]
	v_lshlrev_b64 v[64:65], 14, v[64:65]
	v_lshlrev_b64 v[66:67], 14, v[66:67]
	v_lshlrev_b64 v[68:69], 14, v[68:69]
	v_lshlrev_b64 v[70:71], 14, v[70:71]
	v_lshl_add_u64 v[104:105], v[74:75], 1, v[72:73]
	v_ashrrev_i32_e32 v77, 31, v76
	v_ashrrev_i32_e32 v79, 31, v78
	v_ashrrev_i32_e32 v81, 31, v80
	v_ashrrev_i32_e32 v83, 31, v82
	v_ashrrev_i32_e32 v85, 31, v84
	v_ashrrev_i32_e32 v87, 31, v86
	v_ashrrev_i32_e32 v89, 31, v88
	v_lshl_add_u64 v[40:41], v[90:91], 0, v[40:41]
	v_lshl_add_u64 v[74:75], v[90:91], 0, v[42:43]
	v_lshl_add_u64 v[92:93], v[90:91], 0, v[44:45]
	v_lshl_add_u64 v[94:95], v[90:91], 0, v[46:47]
	v_lshl_add_u64 v[96:97], v[90:91], 0, v[48:49]
	v_lshl_add_u64 v[98:99], v[90:91], 0, v[50:51]
	v_lshl_add_u64 v[100:101], v[90:91], 0, v[52:53]
	v_lshl_add_u64 v[102:103], v[90:91], 0, v[54:55]
	v_lshl_add_u64 v[106:107], v[90:91], 0, v[56:57]
	v_lshl_add_u64 v[108:109], v[90:91], 0, v[58:59]
	v_lshl_add_u64 v[110:111], v[90:91], 0, v[60:61]
	v_lshl_add_u64 v[112:113], v[90:91], 0, v[62:63]
	v_lshl_add_u64 v[114:115], v[90:91], 0, v[64:65]
	v_lshl_add_u64 v[116:117], v[90:91], 0, v[66:67]
	v_lshl_add_u64 v[118:119], v[90:91], 0, v[68:69]
	v_lshl_add_u64 v[120:121], v[90:91], 0, v[70:71]
	v_lshl_add_u64 v[122:123], v[76:77], 1, v[72:73]
	v_lshl_add_u64 v[124:125], v[78:79], 1, v[72:73]
	v_lshl_add_u64 v[126:127], v[80:81], 1, v[72:73]
	v_lshl_add_u64 v[128:129], v[82:83], 1, v[72:73]
	v_lshl_add_u64 v[130:131], v[84:85], 1, v[72:73]
	v_lshl_add_u64 v[132:133], v[86:87], 1, v[72:73]
	v_lshl_add_u64 v[134:135], v[88:89], 1, v[72:73]
	global_load_dwordx4 v[40:43], v[40:41], off nt
	s_nop 0
	global_load_dwordx4 v[44:47], v[74:75], off nt
	global_load_dwordx4 v[48:51], v[92:93], off nt
	global_load_dwordx4 v[52:55], v[94:95], off nt
	global_load_dwordx4 v[56:59], v[96:97], off nt
	global_load_dwordx4 v[60:63], v[98:99], off nt
	global_load_dwordx4 v[64:67], v[100:101], off nt
	global_load_dwordx4 v[68:71], v[102:103], off nt
	global_load_dwordx4 v[72:75], v[106:107], off nt
	global_load_dwordx4 v[76:79], v[108:109], off nt
	global_load_dwordx4 v[80:83], v[110:111], off nt
	global_load_dwordx4 v[84:87], v[112:113], off nt
	global_load_dwordx4 v[88:91], v[114:115], off nt
	global_load_dwordx4 v[92:95], v[116:117], off nt
	global_load_dwordx4 v[96:99], v[118:119], off nt
	global_load_dwordx4 v[100:103], v[120:121], off nt
	s_waitcnt vmcnt(15)
	ds_write2_b32 v8, v40, v41 offset1:1
	ds_write2_b32 v8, v42, v43 offset0:2 offset1:3
	s_waitcnt vmcnt(14)
	ds_write2_b32 v9, v44, v45 offset1:1
	ds_write2_b32 v10, v46, v47 offset1:1
	s_waitcnt vmcnt(13)
	ds_write2_b32 v11, v48, v49 offset1:1
	ds_write2_b32 v12, v50, v51 offset1:1
	s_waitcnt vmcnt(12)
	ds_write2_b32 v13, v52, v53 offset1:1
	ds_write2_b32 v14, v54, v55 offset1:1
	s_waitcnt vmcnt(11)
	ds_write2_b32 v15, v56, v57 offset1:1
	ds_write2_b32 v16, v58, v59 offset1:1
	s_waitcnt vmcnt(10)
	ds_write2_b32 v17, v60, v61 offset1:1
	ds_write2_b32 v18, v62, v63 offset1:1
	s_waitcnt vmcnt(9)
	ds_write2_b32 v19, v64, v65 offset1:1
	ds_write2_b32 v20, v66, v67 offset1:1
	s_waitcnt vmcnt(8)
	ds_write2_b32 v21, v68, v69 offset1:1
	ds_write2_b32 v22, v70, v71 offset1:1
	s_waitcnt vmcnt(7)
	ds_write2_b32 v23, v72, v73 offset1:1
	ds_write2_b32 v24, v74, v75 offset1:1
	s_waitcnt vmcnt(6)
	ds_write2_b32 v25, v76, v77 offset1:1
	ds_write2_b32 v26, v78, v79 offset1:1
	s_waitcnt vmcnt(5)
	ds_write2_b32 v27, v80, v81 offset1:1
	ds_write2_b32 v28, v82, v83 offset1:1
	s_waitcnt vmcnt(4)
	ds_write2_b32 v29, v84, v85 offset1:1
	ds_write2_b32 v30, v86, v87 offset1:1
	s_waitcnt vmcnt(3)
	ds_write2_b32 v31, v88, v89 offset1:1
	ds_write2_b32 v32, v90, v91 offset1:1
	s_waitcnt vmcnt(2)
	ds_write2_b32 v33, v92, v93 offset1:1
	ds_write2_b32 v34, v94, v95 offset1:1
	s_waitcnt vmcnt(1)
	ds_write2_b32 v35, v96, v97 offset1:1
	ds_write2_b32 v36, v98, v99 offset1:1
	s_waitcnt vmcnt(0)
	ds_write2_b32 v37, v100, v101 offset1:1
	ds_write2_b32 v38, v102, v103 offset1:1
	s_waitcnt lgkmcnt(0)
	ds_read2_b32 v[44:45], v6 offset0:65 offset1:73
	ds_read2_b32 v[46:47], v6 offset1:8
	ds_read2_b32 v[48:49], v6 offset0:130 offset1:138
	ds_read2_b32 v[50:51], v6 offset0:195 offset1:203
	ds_read2_b32 v[52:53], v39 offset0:4 offset1:12
	ds_read2_b32 v[54:55], v39 offset0:69 offset1:77
	ds_read2_b32 v[56:57], v39 offset0:134 offset1:142
	ds_read2_b32 v[58:59], v39 offset0:199 offset1:207
	ds_read2_b32 v[60:61], v6 offset0:81 offset1:89
	ds_read2_b32 v[62:63], v6 offset0:16 offset1:24
	ds_read2_b32 v[64:65], v6 offset0:146 offset1:154
	ds_read2_b32 v[66:67], v6 offset0:211 offset1:219
	ds_read2_b32 v[68:69], v39 offset0:20 offset1:28
	ds_read2_b32 v[70:71], v39 offset0:85 offset1:93
	ds_read2_b32 v[72:73], v39 offset0:150 offset1:158
	ds_read2_b32 v[74:75], v39 offset0:215 offset1:223
	ds_read2_b32 v[76:77], v6 offset0:32 offset1:40
	ds_read2_b32 v[78:79], v6 offset0:97 offset1:105
	ds_read2_b32 v[80:81], v6 offset0:162 offset1:170
	ds_read2_b32 v[82:83], v6 offset0:227 offset1:235
	ds_read2_b32 v[84:85], v39 offset0:36 offset1:44
	ds_read2_b32 v[86:87], v39 offset0:101 offset1:109
	ds_read2_b32 v[88:89], v39 offset0:166 offset1:174
	ds_read2_b32 v[90:91], v39 offset0:231 offset1:239
	ds_read2_b32 v[92:93], v6 offset0:48 offset1:56
	ds_read2_b32 v[94:95], v6 offset0:113 offset1:121
	ds_read2_b32 v[96:97], v6 offset0:178 offset1:186
	ds_read2_b32 v[98:99], v6 offset0:243 offset1:251
	ds_read2_b32 v[100:101], v39 offset0:52 offset1:60
	ds_read2_b32 v[102:103], v39 offset0:117 offset1:125
	ds_read2_b32 v[106:107], v39 offset0:182 offset1:190
	ds_read2_b32 v[108:109], v39 offset0:247 offset1:255
	s_waitcnt lgkmcnt(14)
	v_cvt_pk_bf16_f32 v40, v46, v44
	v_cvt_pk_bf16_f32 v41, v48, v50
	v_cvt_pk_bf16_f32 v42, v52, v54
	v_cvt_pk_bf16_f32 v43, v56, v58
	v_cvt_pk_bf16_f32 v44, v47, v45
	v_cvt_pk_bf16_f32 v45, v49, v51
	v_cvt_pk_bf16_f32 v46, v53, v55
	v_cvt_pk_bf16_f32 v47, v57, v59
	v_cvt_pk_bf16_f32 v48, v62, v60
	v_cvt_pk_bf16_f32 v49, v64, v66
	v_cvt_pk_bf16_f32 v50, v68, v70
	v_cvt_pk_bf16_f32 v51, v72, v74
	v_cvt_pk_bf16_f32 v52, v63, v61
	v_cvt_pk_bf16_f32 v53, v65, v67
	v_cvt_pk_bf16_f32 v54, v69, v71
	v_cvt_pk_bf16_f32 v55, v73, v75
	v_cvt_pk_bf16_f32 v56, v76, v78
	s_waitcnt lgkmcnt(12)
	v_cvt_pk_bf16_f32 v57, v80, v82
	s_waitcnt lgkmcnt(10)
	v_cvt_pk_bf16_f32 v58, v84, v86
	s_waitcnt lgkmcnt(8)
	v_cvt_pk_bf16_f32 v59, v88, v90
	v_cvt_pk_bf16_f32 v60, v77, v79
	v_cvt_pk_bf16_f32 v61, v81, v83
	v_cvt_pk_bf16_f32 v62, v85, v87
	v_cvt_pk_bf16_f32 v63, v89, v91
	s_waitcnt lgkmcnt(6)
	v_cvt_pk_bf16_f32 v64, v92, v94
	s_waitcnt lgkmcnt(4)
	v_cvt_pk_bf16_f32 v65, v96, v98
	s_waitcnt lgkmcnt(2)
	v_cvt_pk_bf16_f32 v66, v100, v102
	s_waitcnt lgkmcnt(0)
	v_cvt_pk_bf16_f32 v67, v106, v108
	v_cvt_pk_bf16_f32 v68, v93, v95
	v_cvt_pk_bf16_f32 v69, v97, v99
	v_cvt_pk_bf16_f32 v70, v101, v103
	v_cvt_pk_bf16_f32 v71, v107, v109
	global_store_dwordx4 v[104:105], v[40:43], off
	global_store_dwordx4 v[122:123], v[44:47], off
	global_store_dwordx4 v[124:125], v[48:51], off
	global_store_dwordx4 v[126:127], v[52:55], off
	global_store_dwordx4 v[128:129], v[56:59], off
	global_store_dwordx4 v[130:131], v[60:63], off
	global_store_dwordx4 v[132:133], v[64:67], off
	global_store_dwordx4 v[134:135], v[68:71], off
	s_waitcnt lgkmcnt(0)
	s_add_i32 s1, s1, s0
	s_add_i32 s3, s3, s6
	s_cmpk_lt_i32 s1, 0x2b00
	v_add_u32_e32 v7, s2, v7
	s_cbranch_scc1 .LBB0_306

.LBB0_506:
	s_mul_hi_i32 s0, s4, 0xb68d3135
	s_add_i32 s0, s0, s4
	s_lshr_b32 s1, s0, 31
	s_ashr_i32 s8, s0, 8
	s_add_i32 s8, s8, s1
	s_mul_i32 s0, s8, 0xffffa640
	s_add_i32 s10, s5, s0
	s_lshl_b32 s0, s8, 6
	v_or_b32_e32 v70, s0, v1
	s_ashr_i32 s11, s10, 31
	v_lshl_add_u64 v[2:3], s[10:11], 2, v[66:67]
	v_or_b32_e32 v6, 4, v70
	v_mad_i64_i32 v[4:5], s[10:11], v70, s7, v[2:3]
	v_mad_i64_i32 v[6:7], s[10:11], v6, s7, v[2:3]
	global_load_dwordx4 v[62:65], v[4:5], off nt
	global_load_dwordx4 v[50:53], v[6:7], off nt
	v_or_b32_e32 v4, 8, v70
	v_or_b32_e32 v6, 12, v70
	v_mad_i64_i32 v[4:5], s[10:11], v4, s7, v[2:3]
	v_mad_i64_i32 v[6:7], s[10:11], v6, s7, v[2:3]
	global_load_dwordx4 v[58:61], v[4:5], off nt
	global_load_dwordx4 v[42:45], v[6:7], off nt
	v_or_b32_e32 v4, 16, v70
	v_or_b32_e32 v6, 20, v70
	v_mad_i64_i32 v[4:5], s[10:11], v4, s7, v[2:3]
	v_mad_i64_i32 v[6:7], s[10:11], v6, s7, v[2:3]
	global_load_dwordx4 v[54:57], v[4:5], off nt
	global_load_dwordx4 v[34:37], v[6:7], off nt
	v_or_b32_e32 v4, 24, v70
	v_or_b32_e32 v6, 28, v70
	v_mad_i64_i32 v[4:5], s[10:11], v4, s7, v[2:3]
	v_mad_i64_i32 v[6:7], s[10:11], v6, s7, v[2:3]
	global_load_dwordx4 v[46:49], v[4:5], off nt
	global_load_dwordx4 v[26:29], v[6:7], off nt
	v_or_b32_e32 v4, 32, v70
	v_or_b32_e32 v6, 36, v70
	v_mad_i64_i32 v[4:5], s[10:11], v4, s7, v[2:3]
	v_mad_i64_i32 v[6:7], s[10:11], v6, s7, v[2:3]
	global_load_dwordx4 v[38:41], v[4:5], off nt
	global_load_dwordx4 v[18:21], v[6:7], off nt
	v_or_b32_e32 v4, 40, v70
	v_or_b32_e32 v6, 44, v70
	v_mad_i64_i32 v[4:5], s[10:11], v4, s7, v[2:3]
	v_mad_i64_i32 v[6:7], s[10:11], v6, s7, v[2:3]
	global_load_dwordx4 v[30:33], v[4:5], off nt
	global_load_dwordx4 v[10:13], v[6:7], off nt
	v_or_b32_e32 v4, 48, v70
	v_or_b32_e32 v6, 52, v70
	v_mad_i64_i32 v[4:5], s[10:11], v4, s7, v[2:3]
	v_mad_i64_i32 v[6:7], s[10:11], v6, s7, v[2:3]
	global_load_dwordx4 v[22:25], v[4:5], off nt
	s_nop 0
	global_load_dwordx4 v[6:9], v[6:7], off nt
	v_or_b32_e32 v4, 56, v70
	v_or_b32_e32 v14, 60, v70
	v_mad_i64_i32 v[4:5], s[10:11], v4, s7, v[2:3]
	v_mad_i64_i32 v[2:3], s[10:11], v14, s7, v[2:3]
	global_load_dwordx4 v[14:17], v[4:5], off nt
	s_nop 0
	global_load_dwordx4 v[2:5], v[2:3], off nt
	s_and_b64 vcc, exec, s[2:3]
	s_cbranch_vccnz .LBB0_505
	v_ashrrev_i32_e32 v71, 31, v70
	v_lshl_add_u64 v[70:71], v[70:71], 2, s[66:67]
	global_load_dword v76, v[70:71], off
	global_load_dword v78, v[70:71], off offset:16
	global_load_dword v80, v[70:71], off offset:32
	global_load_dword v82, v[70:71], off offset:48
	global_load_dword v84, v[70:71], off offset:64
	global_load_dword v86, v[70:71], off offset:80
	global_load_dword v88, v[70:71], off offset:96
	global_load_dword v90, v[70:71], off offset:112
	global_load_dword v92, v[70:71], off offset:128
	global_load_dword v94, v[70:71], off offset:144
	global_load_dword v96, v[70:71], off offset:160
	global_load_dword v98, v[70:71], off offset:176
	global_load_dword v100, v[70:71], off offset:192
	global_load_dword v102, v[70:71], off offset:208
	global_load_dword v104, v[70:71], off offset:224
	s_nop 0
	global_load_dword v70, v[70:71], off offset:240
	s_waitcnt vmcnt(15)
	v_pk_mul_f32 v[64:65], v[64:65], v[76:77] op_sel_hi:[1,0]
	v_pk_mul_f32 v[62:63], v[62:63], v[76:77] op_sel_hi:[1,0]
	s_waitcnt vmcnt(14)
	v_pk_mul_f32 v[52:53], v[52:53], v[78:79] op_sel_hi:[1,0]
	v_pk_mul_f32 v[50:51], v[50:51], v[78:79] op_sel_hi:[1,0]
	s_waitcnt vmcnt(13)
	v_pk_mul_f32 v[60:61], v[60:61], v[80:81] op_sel_hi:[1,0]
	v_pk_mul_f32 v[58:59], v[58:59], v[80:81] op_sel_hi:[1,0]
	s_waitcnt vmcnt(12)
	v_pk_mul_f32 v[44:45], v[44:45], v[82:83] op_sel_hi:[1,0]
	v_pk_mul_f32 v[42:43], v[42:43], v[82:83] op_sel_hi:[1,0]
	s_waitcnt vmcnt(11)
	v_pk_mul_f32 v[56:57], v[56:57], v[84:85] op_sel_hi:[1,0]
	v_pk_mul_f32 v[54:55], v[54:55], v[84:85] op_sel_hi:[1,0]
	s_waitcnt vmcnt(10)
	v_pk_mul_f32 v[36:37], v[36:37], v[86:87] op_sel_hi:[1,0]
	v_pk_mul_f32 v[34:35], v[34:35], v[86:87] op_sel_hi:[1,0]
	s_waitcnt vmcnt(9)
	v_pk_mul_f32 v[48:49], v[48:49], v[88:89] op_sel_hi:[1,0]
	v_pk_mul_f32 v[46:47], v[46:47], v[88:89] op_sel_hi:[1,0]
	s_waitcnt vmcnt(8)
	v_pk_mul_f32 v[28:29], v[28:29], v[90:91] op_sel_hi:[1,0]
	v_pk_mul_f32 v[26:27], v[26:27], v[90:91] op_sel_hi:[1,0]
	s_waitcnt vmcnt(7)
	v_pk_mul_f32 v[40:41], v[40:41], v[92:93] op_sel_hi:[1,0]
	v_pk_mul_f32 v[38:39], v[38:39], v[92:93] op_sel_hi:[1,0]
	s_waitcnt vmcnt(6)
	v_pk_mul_f32 v[20:21], v[20:21], v[94:95] op_sel_hi:[1,0]
	v_pk_mul_f32 v[18:19], v[18:19], v[94:95] op_sel_hi:[1,0]
	s_waitcnt vmcnt(5)
	v_pk_mul_f32 v[32:33], v[32:33], v[96:97] op_sel_hi:[1,0]
	v_pk_mul_f32 v[30:31], v[30:31], v[96:97] op_sel_hi:[1,0]
	s_waitcnt vmcnt(4)
	v_pk_mul_f32 v[12:13], v[12:13], v[98:99] op_sel_hi:[1,0]
	v_pk_mul_f32 v[10:11], v[10:11], v[98:99] op_sel_hi:[1,0]
	s_waitcnt vmcnt(3)
	v_pk_mul_f32 v[24:25], v[24:25], v[100:101] op_sel_hi:[1,0]
	v_pk_mul_f32 v[22:23], v[22:23], v[100:101] op_sel_hi:[1,0]
	s_waitcnt vmcnt(2)
	v_pk_mul_f32 v[8:9], v[8:9], v[102:103] op_sel_hi:[1,0]
	v_pk_mul_f32 v[6:7], v[6:7], v[102:103] op_sel_hi:[1,0]
	s_waitcnt vmcnt(1)
	v_pk_mul_f32 v[16:17], v[16:17], v[104:105] op_sel_hi:[1,0]
	v_pk_mul_f32 v[14:15], v[14:15], v[104:105] op_sel_hi:[1,0]
	s_waitcnt vmcnt(0)
	v_pk_mul_f32 v[4:5], v[4:5], v[70:71] op_sel_hi:[1,0]
	v_pk_mul_f32 v[2:3], v[2:3], v[70:71] op_sel_hi:[1,0]
	s_branch .LBB0_505

.LBB0_1128:
	s_ashr_i32 s8, s4, 31
	s_lshr_b32 s8, s8, 26
	s_add_i32 s8, s4, s8
	s_lshl_b32 s9, s8, 6
	s_andn2_b32 s8, s8, 63
	s_and_b32 s10, s9, 0xfffff000
	v_or_b32_e32 v40, s8, v204
	s_sub_i32 s10, s5, s10
	v_or_b32_e32 v42, 4, v40
	v_or_b32_e32 v44, 8, v40
	v_or_b32_e32 v46, 12, v40
	v_or_b32_e32 v48, 16, v40
	v_or_b32_e32 v50, 20, v40
	v_or_b32_e32 v52, 24, v40
	v_or_b32_e32 v54, 28, v40
	v_or_b32_e32 v56, 32, v40
	v_or_b32_e32 v58, 36, v40
	v_or_b32_e32 v60, 40, v40
	v_or_b32_e32 v62, 44, v40
	v_or_b32_e32 v64, 48, v40
	v_or_b32_e32 v66, 52, v40
	v_or_b32_e32 v68, 56, v40
	v_ashrrev_i32_e32 v41, 31, v40
	v_or_b32_e32 v70, 60, v40
	s_ashr_i32 s11, s10, 31
	v_ashrrev_i32_e32 v43, 31, v42
	v_ashrrev_i32_e32 v45, 31, v44
	v_ashrrev_i32_e32 v47, 31, v46
	v_ashrrev_i32_e32 v49, 31, v48
	v_ashrrev_i32_e32 v51, 31, v50
	v_ashrrev_i32_e32 v53, 31, v52
	v_ashrrev_i32_e32 v55, 31, v54
	v_ashrrev_i32_e32 v57, 31, v56
	v_ashrrev_i32_e32 v59, 31, v58
	v_ashrrev_i32_e32 v61, 31, v60
	v_ashrrev_i32_e32 v63, 31, v62
	v_ashrrev_i32_e32 v65, 31, v64
	v_ashrrev_i32_e32 v67, 31, v66
	v_ashrrev_i32_e32 v69, 31, v68
	v_lshlrev_b64 v[40:41], 14, v[40:41]
	v_ashrrev_i32_e32 v71, 31, v70
	v_add_u32_e32 v72, s10, v6
	v_lshl_add_u64 v[74:75], s[10:11], 2, v[2:3]
	v_lshlrev_b64 v[42:43], 14, v[42:43]
	v_lshlrev_b64 v[44:45], 14, v[44:45]
	v_lshlrev_b64 v[46:47], 14, v[46:47]
	v_lshlrev_b64 v[48:49], 14, v[48:49]
	v_lshlrev_b64 v[50:51], 14, v[50:51]
	v_lshlrev_b64 v[52:53], 14, v[52:53]
	v_lshlrev_b64 v[54:55], 14, v[54:55]
	v_lshlrev_b64 v[56:57], 14, v[56:57]
	v_lshlrev_b64 v[58:59], 14, v[58:59]
	v_lshlrev_b64 v[60:61], 14, v[60:61]
	v_lshlrev_b64 v[62:63], 14, v[62:63]
	v_lshlrev_b64 v[64:65], 14, v[64:65]
	v_lshlrev_b64 v[66:67], 14, v[66:67]
	v_lshlrev_b64 v[68:69], 14, v[68:69]
	v_lshlrev_b64 v[70:71], 14, v[70:71]
	v_ashrrev_i32_e32 v73, 31, v72
	v_lshl_add_u64 v[40:41], v[74:75], 0, v[40:41]
	v_lshl_add_u64 v[76:77], v[74:75], 0, v[42:43]
	v_lshl_add_u64 v[78:79], v[74:75], 0, v[44:45]
	v_lshl_add_u64 v[80:81], v[74:75], 0, v[46:47]
	v_lshl_add_u64 v[82:83], v[74:75], 0, v[48:49]
	v_lshl_add_u64 v[84:85], v[74:75], 0, v[50:51]
	v_lshl_add_u64 v[86:87], v[74:75], 0, v[52:53]
	v_lshl_add_u64 v[88:89], v[74:75], 0, v[54:55]
	v_lshl_add_u64 v[90:91], v[74:75], 0, v[56:57]
	v_lshl_add_u64 v[92:93], v[74:75], 0, v[58:59]
	v_lshl_add_u64 v[94:95], v[74:75], 0, v[60:61]
	v_lshl_add_u64 v[96:97], v[74:75], 0, v[62:63]
	v_lshl_add_u64 v[98:99], v[74:75], 0, v[64:65]
	v_lshl_add_u64 v[100:101], v[74:75], 0, v[66:67]
	v_lshl_add_u64 v[102:103], v[74:75], 0, v[68:69]
	v_add_u32_e32 v106, 8, v72
	v_add_u32_e32 v108, 16, v72
	v_add_u32_e32 v110, 24, v72
	v_add_u32_e32 v112, 32, v72
	v_add_u32_e32 v114, 40, v72
	v_add_u32_e32 v116, 48, v72
	v_add_u32_e32 v118, 56, v72
	v_lshl_add_u64 v[120:121], v[74:75], 0, v[70:71]
	v_lshlrev_b64 v[122:123], 13, v[72:73]
	global_load_dwordx4 v[40:43], v[40:41], off nt
	s_nop 0
	global_load_dwordx4 v[44:47], v[76:77], off nt
	global_load_dwordx4 v[48:51], v[78:79], off nt
	global_load_dwordx4 v[52:55], v[80:81], off nt
	global_load_dwordx4 v[56:59], v[82:83], off nt
	global_load_dwordx4 v[60:63], v[84:85], off nt
	global_load_dwordx4 v[64:67], v[86:87], off nt
	global_load_dwordx4 v[68:71], v[88:89], off nt
	global_load_dwordx4 v[72:75], v[90:91], off nt
	global_load_dwordx4 v[76:79], v[92:93], off nt
	global_load_dwordx4 v[80:83], v[94:95], off nt
	s_nop 0
	global_load_dwordx4 v[84:87], v[96:97], off nt
	global_load_dwordx4 v[88:91], v[98:99], off nt
	global_load_dwordx4 v[92:95], v[100:101], off nt
	s_nop 0
	global_load_dwordx4 v[96:99], v[102:103], off nt
	s_nop 0
	global_load_dwordx4 v[100:103], v[120:121], off nt
	s_ashr_i32 s9, s8, 31
	v_ashrrev_i32_e32 v107, 31, v106
	v_ashrrev_i32_e32 v109, 31, v108
	v_ashrrev_i32_e32 v111, 31, v110
	v_ashrrev_i32_e32 v113, 31, v112
	s_waitcnt vmcnt(15)
	ds_write2_b32 v8, v40, v41 offset1:1
	ds_write2_b32 v8, v42, v43 offset0:2 offset1:3
	s_waitcnt vmcnt(14)
	ds_write2_b32 v9, v44, v45 offset1:1
	ds_write2_b32 v10, v46, v47 offset1:1
	s_waitcnt vmcnt(13)
	ds_write2_b32 v11, v48, v49 offset1:1
	ds_write2_b32 v12, v50, v51 offset1:1
	s_waitcnt vmcnt(12)
	ds_write2_b32 v13, v52, v53 offset1:1
	ds_write2_b32 v14, v54, v55 offset1:1
	s_waitcnt vmcnt(11)
	ds_write2_b32 v15, v56, v57 offset1:1
	ds_write2_b32 v16, v58, v59 offset1:1
	s_waitcnt vmcnt(10)
	ds_write2_b32 v17, v60, v61 offset1:1
	ds_write2_b32 v18, v62, v63 offset1:1
	s_waitcnt vmcnt(9)
	ds_write2_b32 v19, v64, v65 offset1:1
	ds_write2_b32 v20, v66, v67 offset1:1
	s_waitcnt vmcnt(8)
	ds_write2_b32 v21, v68, v69 offset1:1
	ds_write2_b32 v22, v70, v71 offset1:1
	s_waitcnt vmcnt(7)
	ds_write2_b32 v23, v72, v73 offset1:1
	ds_write2_b32 v24, v74, v75 offset1:1
	s_waitcnt vmcnt(6)
	ds_write2_b32 v25, v76, v77 offset1:1
	ds_write2_b32 v26, v78, v79 offset1:1
	s_waitcnt vmcnt(5)
	ds_write2_b32 v27, v80, v81 offset1:1
	ds_write2_b32 v28, v82, v83 offset1:1
	s_waitcnt vmcnt(4)
	ds_write2_b32 v29, v84, v85 offset1:1
	ds_write2_b32 v30, v86, v87 offset1:1
	s_waitcnt vmcnt(3)
	ds_write2_b32 v31, v88, v89 offset1:1
	ds_write2_b32 v32, v90, v91 offset1:1
	s_waitcnt vmcnt(2)
	ds_write2_b32 v33, v92, v93 offset1:1
	ds_write2_b32 v34, v94, v95 offset1:1
	s_waitcnt vmcnt(1)
	ds_write2_b32 v35, v96, v97 offset1:1
	ds_write2_b32 v36, v98, v99 offset1:1
	s_waitcnt vmcnt(0)
	ds_write2_b32 v37, v100, v101 offset1:1
	ds_write2_b32 v38, v102, v103 offset1:1
	v_ashrrev_i32_e32 v115, 31, v114
	v_ashrrev_i32_e32 v117, 31, v116
	v_ashrrev_i32_e32 v119, 31, v118
	s_waitcnt lgkmcnt(0)
	v_lshl_add_u64 v[104:105], s[8:9], 1, v[4:5]
	v_lshlrev_b64 v[106:107], 13, v[106:107]
	v_lshlrev_b64 v[108:109], 13, v[108:109]
	v_lshlrev_b64 v[110:111], 13, v[110:111]
	v_lshlrev_b64 v[112:113], 13, v[112:113]
	v_lshlrev_b64 v[114:115], 13, v[114:115]
	v_lshlrev_b64 v[116:117], 13, v[116:117]
	v_lshlrev_b64 v[118:119], 13, v[118:119]
	v_lshl_add_u64 v[120:121], v[104:105], 0, v[122:123]
	v_lshl_add_u64 v[106:107], v[104:105], 0, v[106:107]
	v_lshl_add_u64 v[108:109], v[104:105], 0, v[108:109]
	v_lshl_add_u64 v[110:111], v[104:105], 0, v[110:111]
	v_lshl_add_u64 v[112:113], v[104:105], 0, v[112:113]
	v_lshl_add_u64 v[114:115], v[104:105], 0, v[114:115]
	v_lshl_add_u64 v[116:117], v[104:105], 0, v[116:117]
	v_lshl_add_u64 v[104:105], v[104:105], 0, v[118:119]
	ds_read2_b32 v[44:45], v7 offset0:65 offset1:73
	ds_read2_b32 v[46:47], v7 offset1:8
	ds_read2_b32 v[48:49], v7 offset0:130 offset1:138
	ds_read2_b32 v[50:51], v7 offset0:195 offset1:203
	ds_read2_b32 v[52:53], v39 offset0:4 offset1:12
	ds_read2_b32 v[54:55], v39 offset0:69 offset1:77
	ds_read2_b32 v[56:57], v39 offset0:134 offset1:142
	ds_read2_b32 v[58:59], v39 offset0:199 offset1:207
	ds_read2_b32 v[60:61], v7 offset0:81 offset1:89
	ds_read2_b32 v[62:63], v7 offset0:16 offset1:24
	ds_read2_b32 v[64:65], v7 offset0:146 offset1:154
	ds_read2_b32 v[66:67], v7 offset0:211 offset1:219
	ds_read2_b32 v[68:69], v39 offset0:20 offset1:28
	ds_read2_b32 v[70:71], v39 offset0:85 offset1:93
	ds_read2_b32 v[72:73], v39 offset0:150 offset1:158
	ds_read2_b32 v[74:75], v39 offset0:215 offset1:223
	ds_read2_b32 v[76:77], v7 offset0:32 offset1:40
	ds_read2_b32 v[78:79], v7 offset0:97 offset1:105
	ds_read2_b32 v[80:81], v7 offset0:162 offset1:170
	ds_read2_b32 v[82:83], v7 offset0:227 offset1:235
	ds_read2_b32 v[84:85], v39 offset0:36 offset1:44
	ds_read2_b32 v[86:87], v39 offset0:101 offset1:109
	ds_read2_b32 v[88:89], v39 offset0:166 offset1:174
	ds_read2_b32 v[90:91], v39 offset0:231 offset1:239
	ds_read2_b32 v[92:93], v7 offset0:48 offset1:56
	ds_read2_b32 v[94:95], v7 offset0:113 offset1:121
	ds_read2_b32 v[96:97], v7 offset0:178 offset1:186
	ds_read2_b32 v[98:99], v7 offset0:243 offset1:251
	ds_read2_b32 v[100:101], v39 offset0:52 offset1:60
	ds_read2_b32 v[102:103], v39 offset0:117 offset1:125
	ds_read2_b32 v[118:119], v39 offset0:182 offset1:190
	ds_read2_b32 v[122:123], v39 offset0:247 offset1:255
	s_waitcnt lgkmcnt(14)
	v_cvt_pk_bf16_f32 v40, v46, v44
	v_cvt_pk_bf16_f32 v41, v48, v50
	v_cvt_pk_bf16_f32 v42, v52, v54
	v_cvt_pk_bf16_f32 v43, v56, v58
	v_cvt_pk_bf16_f32 v44, v47, v45
	v_cvt_pk_bf16_f32 v45, v49, v51
	v_cvt_pk_bf16_f32 v46, v53, v55
	v_cvt_pk_bf16_f32 v47, v57, v59
	v_cvt_pk_bf16_f32 v48, v62, v60
	v_cvt_pk_bf16_f32 v49, v64, v66
	v_cvt_pk_bf16_f32 v50, v68, v70
	v_cvt_pk_bf16_f32 v51, v72, v74
	v_cvt_pk_bf16_f32 v52, v63, v61
	v_cvt_pk_bf16_f32 v53, v65, v67
	v_cvt_pk_bf16_f32 v54, v69, v71
	v_cvt_pk_bf16_f32 v55, v73, v75
	v_cvt_pk_bf16_f32 v56, v76, v78
	s_waitcnt lgkmcnt(12)
	v_cvt_pk_bf16_f32 v57, v80, v82
	s_waitcnt lgkmcnt(10)
	v_cvt_pk_bf16_f32 v58, v84, v86
	s_waitcnt lgkmcnt(8)
	v_cvt_pk_bf16_f32 v59, v88, v90
	v_cvt_pk_bf16_f32 v60, v77, v79
	v_cvt_pk_bf16_f32 v61, v81, v83
	v_cvt_pk_bf16_f32 v62, v85, v87
	v_cvt_pk_bf16_f32 v63, v89, v91
	s_waitcnt lgkmcnt(6)
	v_cvt_pk_bf16_f32 v64, v92, v94
	s_waitcnt lgkmcnt(4)
	v_cvt_pk_bf16_f32 v65, v96, v98
	s_waitcnt lgkmcnt(2)
	v_cvt_pk_bf16_f32 v66, v100, v102
	s_waitcnt lgkmcnt(0)
	v_cvt_pk_bf16_f32 v67, v118, v122
	v_cvt_pk_bf16_f32 v68, v93, v95
	v_cvt_pk_bf16_f32 v69, v97, v99
	v_cvt_pk_bf16_f32 v70, v101, v103
	v_cvt_pk_bf16_f32 v71, v119, v123
	global_store_dwordx4 v[120:121], v[40:43], off
	global_store_dwordx4 v[106:107], v[44:47], off
	global_store_dwordx4 v[108:109], v[48:51], off
	global_store_dwordx4 v[110:111], v[52:55], off
	global_store_dwordx4 v[112:113], v[56:59], off
	global_store_dwordx4 v[114:115], v[60:63], off
	global_store_dwordx4 v[116:117], v[64:67], off
	global_store_dwordx4 v[104:105], v[68:71], off
	s_waitcnt lgkmcnt(0)
	s_add_i32 s4, s4, s6
	s_add_i32 s5, s5, s7
	s_cmpk_lt_i32 s4, 0x800
	s_cbranch_scc1 .LBB0_1128

.LBB0_1131:
	s_ashr_i32 s8, s4, 31
	s_lshr_b32 s8, s8, 26
	s_add_i32 s8, s4, s8
	s_lshl_b32 s9, s8, 6
	s_andn2_b32 s8, s8, 63
	s_and_b32 s10, s9, 0xfffff000
	v_or_b32_e32 v40, s8, v204
	s_sub_i32 s10, s5, s10
	v_or_b32_e32 v42, 4, v40
	v_or_b32_e32 v44, 8, v40
	v_or_b32_e32 v46, 12, v40
	v_or_b32_e32 v48, 16, v40
	v_or_b32_e32 v50, 20, v40
	v_or_b32_e32 v52, 24, v40
	v_or_b32_e32 v54, 28, v40
	v_or_b32_e32 v56, 32, v40
	v_or_b32_e32 v58, 36, v40
	v_or_b32_e32 v60, 40, v40
	v_or_b32_e32 v62, 44, v40
	v_or_b32_e32 v64, 48, v40
	v_or_b32_e32 v66, 52, v40
	v_or_b32_e32 v68, 56, v40
	v_ashrrev_i32_e32 v41, 31, v40
	v_or_b32_e32 v70, 60, v40
	s_ashr_i32 s11, s10, 31
	v_ashrrev_i32_e32 v43, 31, v42
	v_ashrrev_i32_e32 v45, 31, v44
	v_ashrrev_i32_e32 v47, 31, v46
	v_ashrrev_i32_e32 v49, 31, v48
	v_ashrrev_i32_e32 v51, 31, v50
	v_ashrrev_i32_e32 v53, 31, v52
	v_ashrrev_i32_e32 v55, 31, v54
	v_ashrrev_i32_e32 v57, 31, v56
	v_ashrrev_i32_e32 v59, 31, v58
	v_ashrrev_i32_e32 v61, 31, v60
	v_ashrrev_i32_e32 v63, 31, v62
	v_ashrrev_i32_e32 v65, 31, v64
	v_ashrrev_i32_e32 v67, 31, v66
	v_ashrrev_i32_e32 v69, 31, v68
	v_lshlrev_b64 v[40:41], 14, v[40:41]
	v_ashrrev_i32_e32 v71, 31, v70
	v_add_u32_e32 v72, s10, v6
	v_lshl_add_u64 v[74:75], s[10:11], 2, v[2:3]
	v_lshlrev_b64 v[42:43], 14, v[42:43]
	v_lshlrev_b64 v[44:45], 14, v[44:45]
	v_lshlrev_b64 v[46:47], 14, v[46:47]
	v_lshlrev_b64 v[48:49], 14, v[48:49]
	v_lshlrev_b64 v[50:51], 14, v[50:51]
	v_lshlrev_b64 v[52:53], 14, v[52:53]
	v_lshlrev_b64 v[54:55], 14, v[54:55]
	v_lshlrev_b64 v[56:57], 14, v[56:57]
	v_lshlrev_b64 v[58:59], 14, v[58:59]
	v_lshlrev_b64 v[60:61], 14, v[60:61]
	v_lshlrev_b64 v[62:63], 14, v[62:63]
	v_lshlrev_b64 v[64:65], 14, v[64:65]
	v_lshlrev_b64 v[66:67], 14, v[66:67]
	v_lshlrev_b64 v[68:69], 14, v[68:69]
	v_lshlrev_b64 v[70:71], 14, v[70:71]
	v_ashrrev_i32_e32 v73, 31, v72
	v_lshl_add_u64 v[40:41], v[74:75], 0, v[40:41]
	v_lshl_add_u64 v[76:77], v[74:75], 0, v[42:43]
	v_lshl_add_u64 v[78:79], v[74:75], 0, v[44:45]
	v_lshl_add_u64 v[80:81], v[74:75], 0, v[46:47]
	v_lshl_add_u64 v[82:83], v[74:75], 0, v[48:49]
	v_lshl_add_u64 v[84:85], v[74:75], 0, v[50:51]
	v_lshl_add_u64 v[86:87], v[74:75], 0, v[52:53]
	v_lshl_add_u64 v[88:89], v[74:75], 0, v[54:55]
	v_lshl_add_u64 v[90:91], v[74:75], 0, v[56:57]
	v_lshl_add_u64 v[92:93], v[74:75], 0, v[58:59]
	v_lshl_add_u64 v[94:95], v[74:75], 0, v[60:61]
	v_lshl_add_u64 v[96:97], v[74:75], 0, v[62:63]
	v_lshl_add_u64 v[98:99], v[74:75], 0, v[64:65]
	v_lshl_add_u64 v[100:101], v[74:75], 0, v[66:67]
	v_lshl_add_u64 v[102:103], v[74:75], 0, v[68:69]
	v_add_u32_e32 v106, 8, v72
	v_add_u32_e32 v108, 16, v72
	v_add_u32_e32 v110, 24, v72
	v_add_u32_e32 v112, 32, v72
	v_add_u32_e32 v114, 40, v72
	v_add_u32_e32 v116, 48, v72
	v_add_u32_e32 v118, 56, v72
	v_lshl_add_u64 v[120:121], v[74:75], 0, v[70:71]
	v_lshlrev_b64 v[122:123], 13, v[72:73]
	global_load_dwordx4 v[40:43], v[40:41], off nt
	s_nop 0
	global_load_dwordx4 v[44:47], v[76:77], off nt
	global_load_dwordx4 v[48:51], v[78:79], off nt
	global_load_dwordx4 v[52:55], v[80:81], off nt
	global_load_dwordx4 v[56:59], v[82:83], off nt
	global_load_dwordx4 v[60:63], v[84:85], off nt
	global_load_dwordx4 v[64:67], v[86:87], off nt
	global_load_dwordx4 v[68:71], v[88:89], off nt
	global_load_dwordx4 v[72:75], v[90:91], off nt
	global_load_dwordx4 v[76:79], v[92:93], off nt
	global_load_dwordx4 v[80:83], v[94:95], off nt
	s_nop 0
	global_load_dwordx4 v[84:87], v[96:97], off nt
	global_load_dwordx4 v[88:91], v[98:99], off nt
	global_load_dwordx4 v[92:95], v[100:101], off nt
	s_nop 0
	global_load_dwordx4 v[96:99], v[102:103], off nt
	s_nop 0
	global_load_dwordx4 v[100:103], v[120:121], off nt
	s_ashr_i32 s9, s8, 31
	v_ashrrev_i32_e32 v107, 31, v106
	v_ashrrev_i32_e32 v109, 31, v108
	v_ashrrev_i32_e32 v111, 31, v110
	v_ashrrev_i32_e32 v113, 31, v112
	s_waitcnt vmcnt(15)
	ds_write2_b32 v8, v40, v41 offset1:1
	ds_write2_b32 v8, v42, v43 offset0:2 offset1:3
	s_waitcnt vmcnt(14)
	ds_write2_b32 v9, v44, v45 offset1:1
	ds_write2_b32 v10, v46, v47 offset1:1
	s_waitcnt vmcnt(13)
	ds_write2_b32 v11, v48, v49 offset1:1
	ds_write2_b32 v12, v50, v51 offset1:1
	s_waitcnt vmcnt(12)
	ds_write2_b32 v13, v52, v53 offset1:1
	ds_write2_b32 v14, v54, v55 offset1:1
	s_waitcnt vmcnt(11)
	ds_write2_b32 v15, v56, v57 offset1:1
	ds_write2_b32 v16, v58, v59 offset1:1
	s_waitcnt vmcnt(10)
	ds_write2_b32 v17, v60, v61 offset1:1
	ds_write2_b32 v18, v62, v63 offset1:1
	s_waitcnt vmcnt(9)
	ds_write2_b32 v19, v64, v65 offset1:1
	ds_write2_b32 v20, v66, v67 offset1:1
	s_waitcnt vmcnt(8)
	ds_write2_b32 v21, v68, v69 offset1:1
	ds_write2_b32 v22, v70, v71 offset1:1
	s_waitcnt vmcnt(7)
	ds_write2_b32 v23, v72, v73 offset1:1
	ds_write2_b32 v24, v74, v75 offset1:1
	s_waitcnt vmcnt(6)
	ds_write2_b32 v25, v76, v77 offset1:1
	ds_write2_b32 v26, v78, v79 offset1:1
	s_waitcnt vmcnt(5)
	ds_write2_b32 v27, v80, v81 offset1:1
	ds_write2_b32 v28, v82, v83 offset1:1
	s_waitcnt vmcnt(4)
	ds_write2_b32 v29, v84, v85 offset1:1
	ds_write2_b32 v30, v86, v87 offset1:1
	s_waitcnt vmcnt(3)
	ds_write2_b32 v31, v88, v89 offset1:1
	ds_write2_b32 v32, v90, v91 offset1:1
	s_waitcnt vmcnt(2)
	ds_write2_b32 v33, v92, v93 offset1:1
	ds_write2_b32 v34, v94, v95 offset1:1
	s_waitcnt vmcnt(1)
	ds_write2_b32 v35, v96, v97 offset1:1
	ds_write2_b32 v36, v98, v99 offset1:1
	s_waitcnt vmcnt(0)
	ds_write2_b32 v37, v100, v101 offset1:1
	ds_write2_b32 v38, v102, v103 offset1:1
	v_ashrrev_i32_e32 v115, 31, v114
	v_ashrrev_i32_e32 v117, 31, v116
	v_ashrrev_i32_e32 v119, 31, v118
	s_waitcnt lgkmcnt(0)
	v_lshl_add_u64 v[104:105], s[8:9], 1, v[4:5]
	v_lshlrev_b64 v[106:107], 13, v[106:107]
	v_lshlrev_b64 v[108:109], 13, v[108:109]
	v_lshlrev_b64 v[110:111], 13, v[110:111]
	v_lshlrev_b64 v[112:113], 13, v[112:113]
	v_lshlrev_b64 v[114:115], 13, v[114:115]
	v_lshlrev_b64 v[116:117], 13, v[116:117]
	v_lshlrev_b64 v[118:119], 13, v[118:119]
	v_lshl_add_u64 v[120:121], v[104:105], 0, v[122:123]
	v_lshl_add_u64 v[106:107], v[104:105], 0, v[106:107]
	v_lshl_add_u64 v[108:109], v[104:105], 0, v[108:109]
	v_lshl_add_u64 v[110:111], v[104:105], 0, v[110:111]
	v_lshl_add_u64 v[112:113], v[104:105], 0, v[112:113]
	v_lshl_add_u64 v[114:115], v[104:105], 0, v[114:115]
	v_lshl_add_u64 v[116:117], v[104:105], 0, v[116:117]
	v_lshl_add_u64 v[104:105], v[104:105], 0, v[118:119]
	ds_read2_b32 v[44:45], v7 offset0:65 offset1:73
	ds_read2_b32 v[46:47], v7 offset1:8
	ds_read2_b32 v[48:49], v7 offset0:130 offset1:138
	ds_read2_b32 v[50:51], v7 offset0:195 offset1:203
	ds_read2_b32 v[52:53], v39 offset0:4 offset1:12
	ds_read2_b32 v[54:55], v39 offset0:69 offset1:77
	ds_read2_b32 v[56:57], v39 offset0:134 offset1:142
	ds_read2_b32 v[58:59], v39 offset0:199 offset1:207
	ds_read2_b32 v[60:61], v7 offset0:81 offset1:89
	ds_read2_b32 v[62:63], v7 offset0:16 offset1:24
	ds_read2_b32 v[64:65], v7 offset0:146 offset1:154
	ds_read2_b32 v[66:67], v7 offset0:211 offset1:219
	ds_read2_b32 v[68:69], v39 offset0:20 offset1:28
	ds_read2_b32 v[70:71], v39 offset0:85 offset1:93
	ds_read2_b32 v[72:73], v39 offset0:150 offset1:158
	ds_read2_b32 v[74:75], v39 offset0:215 offset1:223
	ds_read2_b32 v[76:77], v7 offset0:32 offset1:40
	ds_read2_b32 v[78:79], v7 offset0:97 offset1:105
	ds_read2_b32 v[80:81], v7 offset0:162 offset1:170
	ds_read2_b32 v[82:83], v7 offset0:227 offset1:235
	ds_read2_b32 v[84:85], v39 offset0:36 offset1:44
	ds_read2_b32 v[86:87], v39 offset0:101 offset1:109
	ds_read2_b32 v[88:89], v39 offset0:166 offset1:174
	ds_read2_b32 v[90:91], v39 offset0:231 offset1:239
	ds_read2_b32 v[92:93], v7 offset0:48 offset1:56
	ds_read2_b32 v[94:95], v7 offset0:113 offset1:121
	ds_read2_b32 v[96:97], v7 offset0:178 offset1:186
	ds_read2_b32 v[98:99], v7 offset0:243 offset1:251
	ds_read2_b32 v[100:101], v39 offset0:52 offset1:60
	ds_read2_b32 v[102:103], v39 offset0:117 offset1:125
	ds_read2_b32 v[118:119], v39 offset0:182 offset1:190
	ds_read2_b32 v[122:123], v39 offset0:247 offset1:255
	s_waitcnt lgkmcnt(14)
	v_cvt_pk_bf16_f32 v40, v46, v44
	v_cvt_pk_bf16_f32 v41, v48, v50
	v_cvt_pk_bf16_f32 v42, v52, v54
	v_cvt_pk_bf16_f32 v43, v56, v58
	v_cvt_pk_bf16_f32 v44, v47, v45
	v_cvt_pk_bf16_f32 v45, v49, v51
	v_cvt_pk_bf16_f32 v46, v53, v55
	v_cvt_pk_bf16_f32 v47, v57, v59
	v_cvt_pk_bf16_f32 v48, v62, v60
	v_cvt_pk_bf16_f32 v49, v64, v66
	v_cvt_pk_bf16_f32 v50, v68, v70
	v_cvt_pk_bf16_f32 v51, v72, v74
	v_cvt_pk_bf16_f32 v52, v63, v61
	v_cvt_pk_bf16_f32 v53, v65, v67
	v_cvt_pk_bf16_f32 v54, v69, v71
	v_cvt_pk_bf16_f32 v55, v73, v75
	v_cvt_pk_bf16_f32 v56, v76, v78
	s_waitcnt lgkmcnt(12)
	v_cvt_pk_bf16_f32 v57, v80, v82
	s_waitcnt lgkmcnt(10)
	v_cvt_pk_bf16_f32 v58, v84, v86
	s_waitcnt lgkmcnt(8)
	v_cvt_pk_bf16_f32 v59, v88, v90
	v_cvt_pk_bf16_f32 v60, v77, v79
	v_cvt_pk_bf16_f32 v61, v81, v83
	v_cvt_pk_bf16_f32 v62, v85, v87
	v_cvt_pk_bf16_f32 v63, v89, v91
	s_waitcnt lgkmcnt(6)
	v_cvt_pk_bf16_f32 v64, v92, v94
	s_waitcnt lgkmcnt(4)
	v_cvt_pk_bf16_f32 v65, v96, v98
	s_waitcnt lgkmcnt(2)
	v_cvt_pk_bf16_f32 v66, v100, v102
	s_waitcnt lgkmcnt(0)
	v_cvt_pk_bf16_f32 v67, v118, v122
	v_cvt_pk_bf16_f32 v68, v93, v95
	v_cvt_pk_bf16_f32 v69, v97, v99
	v_cvt_pk_bf16_f32 v70, v101, v103
	v_cvt_pk_bf16_f32 v71, v119, v123
	global_store_dwordx4 v[120:121], v[40:43], off
	global_store_dwordx4 v[106:107], v[44:47], off
	global_store_dwordx4 v[108:109], v[48:51], off
	global_store_dwordx4 v[110:111], v[52:55], off
	global_store_dwordx4 v[112:113], v[56:59], off
	global_store_dwordx4 v[114:115], v[60:63], off
	global_store_dwordx4 v[116:117], v[64:67], off
	global_store_dwordx4 v[104:105], v[68:71], off
	s_waitcnt lgkmcnt(0)
	s_add_i32 s4, s4, s6
	s_add_i32 s5, s5, s7
	s_cmpk_lt_i32 s4, 0x400
	s_cbranch_scc1 .LBB0_1131

.LBB0_1137:
	s_ashr_i32 s8, s4, 31
	s_lshr_b32 s8, s8, 26
	s_add_i32 s8, s4, s8
	s_lshl_b32 s9, s8, 6
	s_andn2_b32 s8, s8, 63
	s_and_b32 s10, s9, 0xfffff000
	v_or_b32_e32 v40, s8, v204
	s_sub_i32 s10, s5, s10
	v_or_b32_e32 v42, 4, v40
	v_or_b32_e32 v44, 8, v40
	v_or_b32_e32 v46, 12, v40
	v_or_b32_e32 v48, 16, v40
	v_or_b32_e32 v50, 20, v40
	v_or_b32_e32 v52, 24, v40
	v_or_b32_e32 v54, 28, v40
	v_or_b32_e32 v56, 32, v40
	v_or_b32_e32 v58, 36, v40
	v_or_b32_e32 v60, 40, v40
	v_or_b32_e32 v62, 44, v40
	v_or_b32_e32 v64, 48, v40
	v_or_b32_e32 v66, 52, v40
	v_or_b32_e32 v68, 56, v40
	v_ashrrev_i32_e32 v41, 31, v40
	v_or_b32_e32 v70, 60, v40
	s_ashr_i32 s11, s10, 31
	v_ashrrev_i32_e32 v43, 31, v42
	v_ashrrev_i32_e32 v45, 31, v44
	v_ashrrev_i32_e32 v47, 31, v46
	v_ashrrev_i32_e32 v49, 31, v48
	v_ashrrev_i32_e32 v51, 31, v50
	v_ashrrev_i32_e32 v53, 31, v52
	v_ashrrev_i32_e32 v55, 31, v54
	v_ashrrev_i32_e32 v57, 31, v56
	v_ashrrev_i32_e32 v59, 31, v58
	v_ashrrev_i32_e32 v61, 31, v60
	v_ashrrev_i32_e32 v63, 31, v62
	v_ashrrev_i32_e32 v65, 31, v64
	v_ashrrev_i32_e32 v67, 31, v66
	v_ashrrev_i32_e32 v69, 31, v68
	v_lshlrev_b64 v[40:41], 14, v[40:41]
	v_ashrrev_i32_e32 v71, 31, v70
	v_add_u32_e32 v72, s10, v6
	v_lshl_add_u64 v[74:75], s[10:11], 2, v[2:3]
	v_lshlrev_b64 v[42:43], 14, v[42:43]
	v_lshlrev_b64 v[44:45], 14, v[44:45]
	v_lshlrev_b64 v[46:47], 14, v[46:47]
	v_lshlrev_b64 v[48:49], 14, v[48:49]
	v_lshlrev_b64 v[50:51], 14, v[50:51]
	v_lshlrev_b64 v[52:53], 14, v[52:53]
	v_lshlrev_b64 v[54:55], 14, v[54:55]
	v_lshlrev_b64 v[56:57], 14, v[56:57]
	v_lshlrev_b64 v[58:59], 14, v[58:59]
	v_lshlrev_b64 v[60:61], 14, v[60:61]
	v_lshlrev_b64 v[62:63], 14, v[62:63]
	v_lshlrev_b64 v[64:65], 14, v[64:65]
	v_lshlrev_b64 v[66:67], 14, v[66:67]
	v_lshlrev_b64 v[68:69], 14, v[68:69]
	v_lshlrev_b64 v[70:71], 14, v[70:71]
	v_ashrrev_i32_e32 v73, 31, v72
	v_lshl_add_u64 v[40:41], v[74:75], 0, v[40:41]
	v_lshl_add_u64 v[76:77], v[74:75], 0, v[42:43]
	v_lshl_add_u64 v[78:79], v[74:75], 0, v[44:45]
	v_lshl_add_u64 v[80:81], v[74:75], 0, v[46:47]
	v_lshl_add_u64 v[82:83], v[74:75], 0, v[48:49]
	v_lshl_add_u64 v[84:85], v[74:75], 0, v[50:51]
	v_lshl_add_u64 v[86:87], v[74:75], 0, v[52:53]
	v_lshl_add_u64 v[88:89], v[74:75], 0, v[54:55]
	v_lshl_add_u64 v[90:91], v[74:75], 0, v[56:57]
	v_lshl_add_u64 v[92:93], v[74:75], 0, v[58:59]
	v_lshl_add_u64 v[94:95], v[74:75], 0, v[60:61]
	v_lshl_add_u64 v[96:97], v[74:75], 0, v[62:63]
	v_lshl_add_u64 v[98:99], v[74:75], 0, v[64:65]
	v_lshl_add_u64 v[100:101], v[74:75], 0, v[66:67]
	v_lshl_add_u64 v[102:103], v[74:75], 0, v[68:69]
	v_add_u32_e32 v106, 8, v72
	v_add_u32_e32 v108, 16, v72
	v_add_u32_e32 v110, 24, v72
	v_add_u32_e32 v112, 32, v72
	v_add_u32_e32 v114, 40, v72
	v_add_u32_e32 v116, 48, v72
	v_add_u32_e32 v118, 56, v72
	v_lshl_add_u64 v[120:121], v[74:75], 0, v[70:71]
	v_lshlrev_b64 v[122:123], 13, v[72:73]
	global_load_dwordx4 v[40:43], v[40:41], off nt
	s_nop 0
	global_load_dwordx4 v[44:47], v[76:77], off nt
	global_load_dwordx4 v[48:51], v[78:79], off nt
	global_load_dwordx4 v[52:55], v[80:81], off nt
	global_load_dwordx4 v[56:59], v[82:83], off nt
	global_load_dwordx4 v[60:63], v[84:85], off nt
	global_load_dwordx4 v[64:67], v[86:87], off nt
	global_load_dwordx4 v[68:71], v[88:89], off nt
	global_load_dwordx4 v[72:75], v[90:91], off nt
	global_load_dwordx4 v[76:79], v[92:93], off nt
	global_load_dwordx4 v[80:83], v[94:95], off nt
	s_nop 0
	global_load_dwordx4 v[84:87], v[96:97], off nt
	global_load_dwordx4 v[88:91], v[98:99], off nt
	global_load_dwordx4 v[92:95], v[100:101], off nt
	s_nop 0
	global_load_dwordx4 v[96:99], v[102:103], off nt
	s_nop 0
	global_load_dwordx4 v[100:103], v[120:121], off nt
	s_ashr_i32 s9, s8, 31
	v_ashrrev_i32_e32 v107, 31, v106
	v_ashrrev_i32_e32 v109, 31, v108
	v_ashrrev_i32_e32 v111, 31, v110
	v_ashrrev_i32_e32 v113, 31, v112
	s_waitcnt vmcnt(15)
	ds_write2_b32 v8, v40, v41 offset1:1
	ds_write2_b32 v8, v42, v43 offset0:2 offset1:3
	s_waitcnt vmcnt(14)
	ds_write2_b32 v9, v44, v45 offset1:1
	ds_write2_b32 v10, v46, v47 offset1:1
	s_waitcnt vmcnt(13)
	ds_write2_b32 v11, v48, v49 offset1:1
	ds_write2_b32 v12, v50, v51 offset1:1
	s_waitcnt vmcnt(12)
	ds_write2_b32 v13, v52, v53 offset1:1
	ds_write2_b32 v14, v54, v55 offset1:1
	s_waitcnt vmcnt(11)
	ds_write2_b32 v15, v56, v57 offset1:1
	ds_write2_b32 v16, v58, v59 offset1:1
	s_waitcnt vmcnt(10)
	ds_write2_b32 v17, v60, v61 offset1:1
	ds_write2_b32 v18, v62, v63 offset1:1
	s_waitcnt vmcnt(9)
	ds_write2_b32 v19, v64, v65 offset1:1
	ds_write2_b32 v20, v66, v67 offset1:1
	s_waitcnt vmcnt(8)
	ds_write2_b32 v21, v68, v69 offset1:1
	ds_write2_b32 v22, v70, v71 offset1:1
	s_waitcnt vmcnt(7)
	ds_write2_b32 v23, v72, v73 offset1:1
	ds_write2_b32 v24, v74, v75 offset1:1
	s_waitcnt vmcnt(6)
	ds_write2_b32 v25, v76, v77 offset1:1
	ds_write2_b32 v26, v78, v79 offset1:1
	s_waitcnt vmcnt(5)
	ds_write2_b32 v27, v80, v81 offset1:1
	ds_write2_b32 v28, v82, v83 offset1:1
	s_waitcnt vmcnt(4)
	ds_write2_b32 v29, v84, v85 offset1:1
	ds_write2_b32 v30, v86, v87 offset1:1
	s_waitcnt vmcnt(3)
	ds_write2_b32 v31, v88, v89 offset1:1
	ds_write2_b32 v32, v90, v91 offset1:1
	s_waitcnt vmcnt(2)
	ds_write2_b32 v33, v92, v93 offset1:1
	ds_write2_b32 v34, v94, v95 offset1:1
	s_waitcnt vmcnt(1)
	ds_write2_b32 v35, v96, v97 offset1:1
	ds_write2_b32 v36, v98, v99 offset1:1
	s_waitcnt vmcnt(0)
	ds_write2_b32 v37, v100, v101 offset1:1
	ds_write2_b32 v38, v102, v103 offset1:1
	v_ashrrev_i32_e32 v115, 31, v114
	v_ashrrev_i32_e32 v117, 31, v116
	v_ashrrev_i32_e32 v119, 31, v118
	s_waitcnt lgkmcnt(0)
	v_lshl_add_u64 v[104:105], s[8:9], 1, v[4:5]
	v_lshlrev_b64 v[106:107], 13, v[106:107]
	v_lshlrev_b64 v[108:109], 13, v[108:109]
	v_lshlrev_b64 v[110:111], 13, v[110:111]
	v_lshlrev_b64 v[112:113], 13, v[112:113]
	v_lshlrev_b64 v[114:115], 13, v[114:115]
	v_lshlrev_b64 v[116:117], 13, v[116:117]
	v_lshlrev_b64 v[118:119], 13, v[118:119]
	v_lshl_add_u64 v[120:121], v[104:105], 0, v[122:123]
	v_lshl_add_u64 v[106:107], v[104:105], 0, v[106:107]
	v_lshl_add_u64 v[108:109], v[104:105], 0, v[108:109]
	v_lshl_add_u64 v[110:111], v[104:105], 0, v[110:111]
	v_lshl_add_u64 v[112:113], v[104:105], 0, v[112:113]
	v_lshl_add_u64 v[114:115], v[104:105], 0, v[114:115]
	v_lshl_add_u64 v[116:117], v[104:105], 0, v[116:117]
	v_lshl_add_u64 v[104:105], v[104:105], 0, v[118:119]
	ds_read2_b32 v[44:45], v7 offset0:65 offset1:73
	ds_read2_b32 v[46:47], v7 offset1:8
	ds_read2_b32 v[48:49], v7 offset0:130 offset1:138
	ds_read2_b32 v[50:51], v7 offset0:195 offset1:203
	ds_read2_b32 v[52:53], v39 offset0:4 offset1:12
	ds_read2_b32 v[54:55], v39 offset0:69 offset1:77
	ds_read2_b32 v[56:57], v39 offset0:134 offset1:142
	ds_read2_b32 v[58:59], v39 offset0:199 offset1:207
	ds_read2_b32 v[60:61], v7 offset0:81 offset1:89
	ds_read2_b32 v[62:63], v7 offset0:16 offset1:24
	ds_read2_b32 v[64:65], v7 offset0:146 offset1:154
	ds_read2_b32 v[66:67], v7 offset0:211 offset1:219
	ds_read2_b32 v[68:69], v39 offset0:20 offset1:28
	ds_read2_b32 v[70:71], v39 offset0:85 offset1:93
	ds_read2_b32 v[72:73], v39 offset0:150 offset1:158
	ds_read2_b32 v[74:75], v39 offset0:215 offset1:223
	ds_read2_b32 v[76:77], v7 offset0:32 offset1:40
	ds_read2_b32 v[78:79], v7 offset0:97 offset1:105
	ds_read2_b32 v[80:81], v7 offset0:162 offset1:170
	ds_read2_b32 v[82:83], v7 offset0:227 offset1:235
	ds_read2_b32 v[84:85], v39 offset0:36 offset1:44
	ds_read2_b32 v[86:87], v39 offset0:101 offset1:109
	ds_read2_b32 v[88:89], v39 offset0:166 offset1:174
	ds_read2_b32 v[90:91], v39 offset0:231 offset1:239
	ds_read2_b32 v[92:93], v7 offset0:48 offset1:56
	ds_read2_b32 v[94:95], v7 offset0:113 offset1:121
	ds_read2_b32 v[96:97], v7 offset0:178 offset1:186
	ds_read2_b32 v[98:99], v7 offset0:243 offset1:251
	ds_read2_b32 v[100:101], v39 offset0:52 offset1:60
	ds_read2_b32 v[102:103], v39 offset0:117 offset1:125
	ds_read2_b32 v[118:119], v39 offset0:182 offset1:190
	ds_read2_b32 v[122:123], v39 offset0:247 offset1:255
	s_waitcnt lgkmcnt(14)
	v_cvt_pk_bf16_f32 v40, v46, v44
	v_cvt_pk_bf16_f32 v41, v48, v50
	v_cvt_pk_bf16_f32 v42, v52, v54
	v_cvt_pk_bf16_f32 v43, v56, v58
	v_cvt_pk_bf16_f32 v44, v47, v45
	v_cvt_pk_bf16_f32 v45, v49, v51
	v_cvt_pk_bf16_f32 v46, v53, v55
	v_cvt_pk_bf16_f32 v47, v57, v59
	v_cvt_pk_bf16_f32 v48, v62, v60
	v_cvt_pk_bf16_f32 v49, v64, v66
	v_cvt_pk_bf16_f32 v50, v68, v70
	v_cvt_pk_bf16_f32 v51, v72, v74
	v_cvt_pk_bf16_f32 v52, v63, v61
	v_cvt_pk_bf16_f32 v53, v65, v67
	v_cvt_pk_bf16_f32 v54, v69, v71
	v_cvt_pk_bf16_f32 v55, v73, v75
	v_cvt_pk_bf16_f32 v56, v76, v78
	s_waitcnt lgkmcnt(12)
	v_cvt_pk_bf16_f32 v57, v80, v82
	s_waitcnt lgkmcnt(10)
	v_cvt_pk_bf16_f32 v58, v84, v86
	s_waitcnt lgkmcnt(8)
	v_cvt_pk_bf16_f32 v59, v88, v90
	v_cvt_pk_bf16_f32 v60, v77, v79
	v_cvt_pk_bf16_f32 v61, v81, v83
	v_cvt_pk_bf16_f32 v62, v85, v87
	v_cvt_pk_bf16_f32 v63, v89, v91
	s_waitcnt lgkmcnt(6)
	v_cvt_pk_bf16_f32 v64, v92, v94
	s_waitcnt lgkmcnt(4)
	v_cvt_pk_bf16_f32 v65, v96, v98
	s_waitcnt lgkmcnt(2)
	v_cvt_pk_bf16_f32 v66, v100, v102
	s_waitcnt lgkmcnt(0)
	v_cvt_pk_bf16_f32 v67, v118, v122
	v_cvt_pk_bf16_f32 v68, v93, v95
	v_cvt_pk_bf16_f32 v69, v97, v99
	v_cvt_pk_bf16_f32 v70, v101, v103
	v_cvt_pk_bf16_f32 v71, v119, v123
	global_store_dwordx4 v[120:121], v[40:43], off
	global_store_dwordx4 v[106:107], v[44:47], off
	global_store_dwordx4 v[108:109], v[48:51], off
	global_store_dwordx4 v[110:111], v[52:55], off
	global_store_dwordx4 v[112:113], v[56:59], off
	global_store_dwordx4 v[114:115], v[60:63], off
	global_store_dwordx4 v[116:117], v[64:67], off
	global_store_dwordx4 v[104:105], v[68:71], off
	s_waitcnt lgkmcnt(0)
	s_add_i32 s4, s4, s6
	s_add_i32 s5, s5, s7
	s_cmpk_lt_i32 s4, 0x1000
	s_cbranch_scc1 .LBB0_1137

.LBB0_1141:
	s_mul_hi_i32 s0, s7, 0x2fa0be83
	s_lshr_b32 s1, s0, 31
	s_ashr_i32 s0, s0, 6
	s_add_i32 s1, s0, s1
	s_mul_i32 s0, s1, 0xffffaa00
	s_add_i32 s4, s8, s0
	s_lshl_b32 s0, s1, 6
	v_or_b32_e32 v70, s0, v204
	s_ashr_i32 s5, s4, 31
	v_lshl_add_u64 v[2:3], s[4:5], 2, v[66:67]
	v_or_b32_e32 v6, 4, v70
	v_mad_i64_i32 v[4:5], s[12:13], v70, s10, v[2:3]
	v_mad_i64_i32 v[6:7], s[12:13], v6, s10, v[2:3]
	global_load_dwordx4 v[62:65], v[4:5], off nt
	global_load_dwordx4 v[50:53], v[6:7], off nt
	v_or_b32_e32 v4, 8, v70
	v_or_b32_e32 v6, 12, v70
	v_mad_i64_i32 v[4:5], s[12:13], v4, s10, v[2:3]
	v_mad_i64_i32 v[6:7], s[12:13], v6, s10, v[2:3]
	global_load_dwordx4 v[58:61], v[4:5], off nt
	global_load_dwordx4 v[42:45], v[6:7], off nt
	v_or_b32_e32 v4, 16, v70
	v_or_b32_e32 v6, 20, v70
	v_mad_i64_i32 v[4:5], s[12:13], v4, s10, v[2:3]
	v_mad_i64_i32 v[6:7], s[12:13], v6, s10, v[2:3]
	global_load_dwordx4 v[54:57], v[4:5], off nt
	global_load_dwordx4 v[34:37], v[6:7], off nt
	v_or_b32_e32 v4, 24, v70
	v_or_b32_e32 v6, 28, v70
	v_mad_i64_i32 v[4:5], s[12:13], v4, s10, v[2:3]
	v_mad_i64_i32 v[6:7], s[12:13], v6, s10, v[2:3]
	global_load_dwordx4 v[46:49], v[4:5], off nt
	global_load_dwordx4 v[26:29], v[6:7], off nt
	v_or_b32_e32 v4, 32, v70
	v_or_b32_e32 v6, 36, v70
	v_mad_i64_i32 v[4:5], s[12:13], v4, s10, v[2:3]
	v_mad_i64_i32 v[6:7], s[12:13], v6, s10, v[2:3]
	global_load_dwordx4 v[38:41], v[4:5], off nt
	global_load_dwordx4 v[18:21], v[6:7], off nt
	v_or_b32_e32 v4, 40, v70
	v_or_b32_e32 v6, 44, v70
	v_mad_i64_i32 v[4:5], s[12:13], v4, s10, v[2:3]
	v_mad_i64_i32 v[6:7], s[12:13], v6, s10, v[2:3]
	global_load_dwordx4 v[30:33], v[4:5], off nt
	global_load_dwordx4 v[10:13], v[6:7], off nt
	v_or_b32_e32 v4, 48, v70
	v_or_b32_e32 v6, 52, v70
	v_mad_i64_i32 v[4:5], s[12:13], v4, s10, v[2:3]
	v_mad_i64_i32 v[6:7], s[12:13], v6, s10, v[2:3]
	global_load_dwordx4 v[22:25], v[4:5], off nt
	s_nop 0
	global_load_dwordx4 v[6:9], v[6:7], off nt
	v_or_b32_e32 v4, 56, v70
	v_or_b32_e32 v14, 60, v70
	v_mad_i64_i32 v[4:5], s[12:13], v4, s10, v[2:3]
	v_mad_i64_i32 v[2:3], s[12:13], v14, s10, v[2:3]
	global_load_dwordx4 v[14:17], v[4:5], off nt
	s_nop 0
	global_load_dwordx4 v[2:5], v[2:3], off nt
	s_and_b64 vcc, exec, s[2:3]
	s_cbranch_vccnz .LBB0_1140
	v_readlane_b32 s72, v254, 44
	v_ashrrev_i32_e32 v71, 31, v70
	v_readlane_b32 s86, v254, 58
	v_readlane_b32 s87, v254, 59
	v_readlane_b32 s73, v254, 45
	v_readlane_b32 s74, v254, 46
	v_lshl_add_u64 v[70:71], v[70:71], 2, s[86:87]
	global_load_dword v82, v[70:71], off
	global_load_dword v84, v[70:71], off offset:16
	global_load_dword v86, v[70:71], off offset:32
	global_load_dword v88, v[70:71], off offset:48
	global_load_dword v90, v[70:71], off offset:64
	global_load_dword v92, v[70:71], off offset:80
	global_load_dword v94, v[70:71], off offset:96
	global_load_dword v96, v[70:71], off offset:112
	global_load_dword v98, v[70:71], off offset:128
	global_load_dword v100, v[70:71], off offset:144
	global_load_dword v102, v[70:71], off offset:160
	global_load_dword v104, v[70:71], off offset:176
	global_load_dword v106, v[70:71], off offset:192
	global_load_dword v108, v[70:71], off offset:208
	global_load_dword v110, v[70:71], off offset:224
	s_nop 0
	global_load_dword v70, v[70:71], off offset:240
	v_readlane_b32 s75, v254, 47
	v_readlane_b32 s76, v254, 48
	v_readlane_b32 s77, v254, 49
	v_readlane_b32 s78, v254, 50
	v_readlane_b32 s79, v254, 51
	v_readlane_b32 s80, v254, 52
	v_readlane_b32 s81, v254, 53
	v_readlane_b32 s82, v254, 54
	v_readlane_b32 s83, v254, 55
	v_readlane_b32 s84, v254, 56
	v_readlane_b32 s85, v254, 57
	s_waitcnt vmcnt(15)
	v_pk_mul_f32 v[64:65], v[64:65], v[82:83] op_sel_hi:[1,0]
	v_pk_mul_f32 v[62:63], v[62:63], v[82:83] op_sel_hi:[1,0]
	s_waitcnt vmcnt(14)
	v_pk_mul_f32 v[52:53], v[52:53], v[84:85] op_sel_hi:[1,0]
	v_pk_mul_f32 v[50:51], v[50:51], v[84:85] op_sel_hi:[1,0]
	s_waitcnt vmcnt(13)
	v_pk_mul_f32 v[60:61], v[60:61], v[86:87] op_sel_hi:[1,0]
	v_pk_mul_f32 v[58:59], v[58:59], v[86:87] op_sel_hi:[1,0]
	s_waitcnt vmcnt(12)
	v_pk_mul_f32 v[44:45], v[44:45], v[88:89] op_sel_hi:[1,0]
	v_pk_mul_f32 v[42:43], v[42:43], v[88:89] op_sel_hi:[1,0]
	s_waitcnt vmcnt(11)
	v_pk_mul_f32 v[56:57], v[56:57], v[90:91] op_sel_hi:[1,0]
	v_pk_mul_f32 v[54:55], v[54:55], v[90:91] op_sel_hi:[1,0]
	s_waitcnt vmcnt(10)
	v_pk_mul_f32 v[36:37], v[36:37], v[92:93] op_sel_hi:[1,0]
	v_pk_mul_f32 v[34:35], v[34:35], v[92:93] op_sel_hi:[1,0]
	s_waitcnt vmcnt(9)
	v_pk_mul_f32 v[48:49], v[48:49], v[94:95] op_sel_hi:[1,0]
	v_pk_mul_f32 v[46:47], v[46:47], v[94:95] op_sel_hi:[1,0]
	s_waitcnt vmcnt(8)
	v_pk_mul_f32 v[28:29], v[28:29], v[96:97] op_sel_hi:[1,0]
	v_pk_mul_f32 v[26:27], v[26:27], v[96:97] op_sel_hi:[1,0]
	s_waitcnt vmcnt(7)
	v_pk_mul_f32 v[40:41], v[40:41], v[98:99] op_sel_hi:[1,0]
	v_pk_mul_f32 v[38:39], v[38:39], v[98:99] op_sel_hi:[1,0]
	s_waitcnt vmcnt(6)
	v_pk_mul_f32 v[20:21], v[20:21], v[100:101] op_sel_hi:[1,0]
	v_pk_mul_f32 v[18:19], v[18:19], v[100:101] op_sel_hi:[1,0]
	s_waitcnt vmcnt(5)
	v_pk_mul_f32 v[32:33], v[32:33], v[102:103] op_sel_hi:[1,0]
	v_pk_mul_f32 v[30:31], v[30:31], v[102:103] op_sel_hi:[1,0]
	s_waitcnt vmcnt(4)
	v_pk_mul_f32 v[12:13], v[12:13], v[104:105] op_sel_hi:[1,0]
	v_pk_mul_f32 v[10:11], v[10:11], v[104:105] op_sel_hi:[1,0]
	s_waitcnt vmcnt(3)
	v_pk_mul_f32 v[24:25], v[24:25], v[106:107] op_sel_hi:[1,0]
	v_pk_mul_f32 v[22:23], v[22:23], v[106:107] op_sel_hi:[1,0]
	s_waitcnt vmcnt(2)
	v_pk_mul_f32 v[8:9], v[8:9], v[108:109] op_sel_hi:[1,0]
	v_pk_mul_f32 v[6:7], v[6:7], v[108:109] op_sel_hi:[1,0]
	s_waitcnt vmcnt(1)
	v_pk_mul_f32 v[16:17], v[16:17], v[110:111] op_sel_hi:[1,0]
	v_pk_mul_f32 v[14:15], v[14:15], v[110:111] op_sel_hi:[1,0]
	s_waitcnt vmcnt(0)
	v_pk_mul_f32 v[4:5], v[4:5], v[70:71] op_sel_hi:[1,0]
	v_pk_mul_f32 v[2:3], v[2:3], v[70:71] op_sel_hi:[1,0]
	s_branch .LBB0_1140

.LBB0_1653:
	s_ashr_i32 s7, s3, 31
	s_lshr_b32 s7, s7, 26
	s_add_i32 s7, s3, s7
	s_ashr_i32 s10, s7, 6
	s_and_b32 s8, s7, 0xffffffc0
	s_lshl_b32 s7, s10, 12
	v_or_b32_e32 v40, s8, v204
	s_mul_i32 s11, s10, 0xfd500000
	s_sub_i32 s10, s5, s7
	v_or_b32_e32 v42, 4, v40
	v_or_b32_e32 v44, 8, v40
	v_or_b32_e32 v46, 12, v40
	v_or_b32_e32 v48, 16, v40
	v_or_b32_e32 v50, 20, v40
	v_ashrrev_i32_e32 v41, 31, v40
	v_or_b32_e32 v52, 24, v40
	v_or_b32_e32 v54, 28, v40
	v_or_b32_e32 v56, 32, v40
	v_or_b32_e32 v58, 36, v40
	v_or_b32_e32 v60, 40, v40
	v_or_b32_e32 v62, 44, v40
	v_or_b32_e32 v64, 48, v40
	v_or_b32_e32 v66, 52, v40
	v_or_b32_e32 v68, 56, v40
	v_or_b32_e32 v70, 60, v40
	v_add_u32_e32 v74, s11, v7
	s_ashr_i32 s11, s10, 31
	v_ashrrev_i32_e32 v43, 31, v42
	v_ashrrev_i32_e32 v45, 31, v44
	v_ashrrev_i32_e32 v47, 31, v46
	v_ashrrev_i32_e32 v49, 31, v48
	v_ashrrev_i32_e32 v51, 31, v50
	s_ashr_i32 s9, s8, 31
	v_lshlrev_b64 v[40:41], 14, v[40:41]
	v_ashrrev_i32_e32 v53, 31, v52
	v_ashrrev_i32_e32 v55, 31, v54
	v_ashrrev_i32_e32 v57, 31, v56
	v_ashrrev_i32_e32 v59, 31, v58
	v_ashrrev_i32_e32 v61, 31, v60
	v_ashrrev_i32_e32 v63, 31, v62
	v_ashrrev_i32_e32 v65, 31, v64
	v_ashrrev_i32_e32 v67, 31, v66
	v_ashrrev_i32_e32 v69, 31, v68
	v_ashrrev_i32_e32 v71, 31, v70
	v_add_u32_e32 v76, 0x15800, v74
	v_add_u32_e32 v78, 0x2b000, v74
	v_add_u32_e32 v80, 0x40800, v74
	v_add_u32_e32 v82, 0x56000, v74
	v_add_u32_e32 v84, 0x6b800, v74
	v_add_u32_e32 v86, 0x81000, v74
	v_add_u32_e32 v88, 0x96800, v74
	v_lshl_add_u64 v[90:91], s[10:11], 2, v[2:3]
	v_lshlrev_b64 v[42:43], 14, v[42:43]
	v_lshlrev_b64 v[44:45], 14, v[44:45]
	v_lshlrev_b64 v[46:47], 14, v[46:47]
	v_lshlrev_b64 v[48:49], 14, v[48:49]
	v_lshlrev_b64 v[50:51], 14, v[50:51]
	v_lshl_add_u64 v[72:73], s[8:9], 1, v[4:5]
	v_ashrrev_i32_e32 v75, 31, v74
	v_lshlrev_b64 v[52:53], 14, v[52:53]
	v_lshlrev_b64 v[54:55], 14, v[54:55]
	v_lshlrev_b64 v[56:57], 14, v[56:57]
	v_lshlrev_b64 v[58:59], 14, v[58:59]
	v_lshlrev_b64 v[60:61], 14, v[60:61]
	v_lshlrev_b64 v[62:63], 14, v[62:63]
	v_lshlrev_b64 v[64:65], 14, v[64:65]
	v_lshlrev_b64 v[66:67], 14, v[66:67]
	v_lshlrev_b64 v[68:69], 14, v[68:69]
	v_lshlrev_b64 v[70:71], 14, v[70:71]
	v_ashrrev_i32_e32 v77, 31, v76
	v_ashrrev_i32_e32 v79, 31, v78
	v_ashrrev_i32_e32 v81, 31, v80
	v_ashrrev_i32_e32 v83, 31, v82
	v_ashrrev_i32_e32 v85, 31, v84
	v_ashrrev_i32_e32 v87, 31, v86
	v_ashrrev_i32_e32 v89, 31, v88
	v_lshl_add_u64 v[92:93], v[90:91], 0, v[40:41]
	v_lshl_add_u64 v[94:95], v[90:91], 0, v[42:43]
	v_lshl_add_u64 v[96:97], v[90:91], 0, v[44:45]
	v_lshl_add_u64 v[98:99], v[90:91], 0, v[46:47]
	v_lshl_add_u64 v[100:101], v[90:91], 0, v[48:49]
	v_lshl_add_u64 v[102:103], v[90:91], 0, v[50:51]
	v_lshl_add_u64 v[104:105], v[74:75], 1, v[72:73]
	v_lshl_add_u64 v[106:107], v[90:91], 0, v[52:53]
	v_lshl_add_u64 v[108:109], v[90:91], 0, v[54:55]
	v_lshl_add_u64 v[110:111], v[90:91], 0, v[56:57]
	v_lshl_add_u64 v[112:113], v[90:91], 0, v[58:59]
	v_lshl_add_u64 v[114:115], v[90:91], 0, v[60:61]
	v_lshl_add_u64 v[116:117], v[90:91], 0, v[62:63]
	v_lshl_add_u64 v[118:119], v[90:91], 0, v[64:65]
	v_lshl_add_u64 v[120:121], v[90:91], 0, v[66:67]
	v_lshl_add_u64 v[122:123], v[90:91], 0, v[68:69]
	v_lshl_add_u64 v[124:125], v[90:91], 0, v[70:71]
	v_lshl_add_u64 v[126:127], v[76:77], 1, v[72:73]
	v_lshl_add_u64 v[128:129], v[78:79], 1, v[72:73]
	v_lshl_add_u64 v[130:131], v[80:81], 1, v[72:73]
	v_lshl_add_u64 v[132:133], v[82:83], 1, v[72:73]
	v_lshl_add_u64 v[134:135], v[84:85], 1, v[72:73]
	v_lshl_add_u64 v[136:137], v[86:87], 1, v[72:73]
	v_lshl_add_u64 v[140:141], v[88:89], 1, v[72:73]
	global_load_dwordx4 v[40:43], v[92:93], off nt
	global_load_dwordx4 v[44:47], v[94:95], off nt
	global_load_dwordx4 v[48:51], v[96:97], off nt
	global_load_dwordx4 v[52:55], v[98:99], off nt
	global_load_dwordx4 v[56:59], v[100:101], off nt
	global_load_dwordx4 v[60:63], v[102:103], off nt
	global_load_dwordx4 v[64:67], v[106:107], off nt
	global_load_dwordx4 v[68:71], v[108:109], off nt
	global_load_dwordx4 v[72:75], v[110:111], off nt
	global_load_dwordx4 v[76:79], v[112:113], off nt
	global_load_dwordx4 v[80:83], v[114:115], off nt
	global_load_dwordx4 v[84:87], v[116:117], off nt
	global_load_dwordx4 v[88:91], v[118:119], off nt
	global_load_dwordx4 v[92:95], v[120:121], off nt
	global_load_dwordx4 v[96:99], v[122:123], off nt
	global_load_dwordx4 v[100:103], v[124:125], off nt
	s_waitcnt vmcnt(15)
	ds_write2_b32 v8, v40, v41 offset1:1
	ds_write2_b32 v8, v42, v43 offset0:2 offset1:3
	s_waitcnt vmcnt(14)
	ds_write2_b32 v9, v44, v45 offset1:1
	ds_write2_b32 v10, v46, v47 offset1:1
	s_waitcnt vmcnt(13)
	ds_write2_b32 v11, v48, v49 offset1:1
	ds_write2_b32 v12, v50, v51 offset1:1
	s_waitcnt vmcnt(12)
	ds_write2_b32 v13, v52, v53 offset1:1
	ds_write2_b32 v14, v54, v55 offset1:1
	s_waitcnt vmcnt(11)
	ds_write2_b32 v15, v56, v57 offset1:1
	ds_write2_b32 v16, v58, v59 offset1:1
	s_waitcnt vmcnt(10)
	ds_write2_b32 v17, v60, v61 offset1:1
	ds_write2_b32 v18, v62, v63 offset1:1
	s_waitcnt vmcnt(9)
	ds_write2_b32 v19, v64, v65 offset1:1
	ds_write2_b32 v20, v66, v67 offset1:1
	s_waitcnt vmcnt(8)
	ds_write2_b32 v21, v68, v69 offset1:1
	ds_write2_b32 v22, v70, v71 offset1:1
	s_waitcnt vmcnt(7)
	ds_write2_b32 v23, v72, v73 offset1:1
	ds_write2_b32 v24, v74, v75 offset1:1
	s_waitcnt vmcnt(6)
	ds_write2_b32 v25, v76, v77 offset1:1
	ds_write2_b32 v26, v78, v79 offset1:1
	s_waitcnt vmcnt(5)
	ds_write2_b32 v27, v80, v81 offset1:1
	ds_write2_b32 v28, v82, v83 offset1:1
	s_waitcnt vmcnt(4)
	ds_write2_b32 v29, v84, v85 offset1:1
	ds_write2_b32 v30, v86, v87 offset1:1
	s_waitcnt vmcnt(3)
	ds_write2_b32 v31, v88, v89 offset1:1
	ds_write2_b32 v32, v90, v91 offset1:1
	s_waitcnt vmcnt(2)
	ds_write2_b32 v33, v92, v93 offset1:1
	ds_write2_b32 v34, v94, v95 offset1:1
	s_waitcnt vmcnt(1)
	ds_write2_b32 v35, v96, v97 offset1:1
	ds_write2_b32 v36, v98, v99 offset1:1
	s_waitcnt vmcnt(0)
	ds_write2_b32 v37, v100, v101 offset1:1
	ds_write2_b32 v38, v102, v103 offset1:1
	s_waitcnt lgkmcnt(0)
	ds_read2_b32 v[44:45], v6 offset0:65 offset1:73
	ds_read2_b32 v[46:47], v6 offset1:8
	ds_read2_b32 v[48:49], v6 offset0:130 offset1:138
	ds_read2_b32 v[50:51], v6 offset0:195 offset1:203
	ds_read2_b32 v[52:53], v39 offset0:4 offset1:12
	ds_read2_b32 v[54:55], v39 offset0:69 offset1:77
	ds_read2_b32 v[56:57], v39 offset0:134 offset1:142
	ds_read2_b32 v[58:59], v39 offset0:199 offset1:207
	ds_read2_b32 v[60:61], v6 offset0:81 offset1:89
	ds_read2_b32 v[62:63], v6 offset0:16 offset1:24
	ds_read2_b32 v[64:65], v6 offset0:146 offset1:154
	ds_read2_b32 v[66:67], v6 offset0:211 offset1:219
	ds_read2_b32 v[68:69], v39 offset0:20 offset1:28
	ds_read2_b32 v[70:71], v39 offset0:85 offset1:93
	ds_read2_b32 v[72:73], v39 offset0:150 offset1:158
	ds_read2_b32 v[74:75], v39 offset0:215 offset1:223
	ds_read2_b32 v[76:77], v6 offset0:32 offset1:40
	ds_read2_b32 v[78:79], v6 offset0:97 offset1:105
	ds_read2_b32 v[80:81], v6 offset0:162 offset1:170
	ds_read2_b32 v[82:83], v6 offset0:227 offset1:235
	ds_read2_b32 v[84:85], v39 offset0:36 offset1:44
	ds_read2_b32 v[86:87], v39 offset0:101 offset1:109
	ds_read2_b32 v[88:89], v39 offset0:166 offset1:174
	ds_read2_b32 v[90:91], v39 offset0:231 offset1:239
	ds_read2_b32 v[92:93], v6 offset0:48 offset1:56
	ds_read2_b32 v[94:95], v6 offset0:113 offset1:121
	ds_read2_b32 v[96:97], v6 offset0:178 offset1:186
	ds_read2_b32 v[98:99], v6 offset0:243 offset1:251
	ds_read2_b32 v[100:101], v39 offset0:52 offset1:60
	ds_read2_b32 v[102:103], v39 offset0:117 offset1:125
	ds_read2_b32 v[106:107], v39 offset0:182 offset1:190
	ds_read2_b32 v[108:109], v39 offset0:247 offset1:255
	s_waitcnt lgkmcnt(14)
	v_cvt_pk_bf16_f32 v40, v46, v44
	v_cvt_pk_bf16_f32 v41, v48, v50
	v_cvt_pk_bf16_f32 v42, v52, v54
	v_cvt_pk_bf16_f32 v43, v56, v58
	v_cvt_pk_bf16_f32 v44, v47, v45
	v_cvt_pk_bf16_f32 v45, v49, v51
	v_cvt_pk_bf16_f32 v46, v53, v55
	v_cvt_pk_bf16_f32 v47, v57, v59
	v_cvt_pk_bf16_f32 v48, v62, v60
	v_cvt_pk_bf16_f32 v49, v64, v66
	v_cvt_pk_bf16_f32 v50, v68, v70
	v_cvt_pk_bf16_f32 v51, v72, v74
	v_cvt_pk_bf16_f32 v52, v63, v61
	v_cvt_pk_bf16_f32 v53, v65, v67
	v_cvt_pk_bf16_f32 v54, v69, v71
	v_cvt_pk_bf16_f32 v55, v73, v75
	v_cvt_pk_bf16_f32 v56, v76, v78
	s_waitcnt lgkmcnt(12)
	v_cvt_pk_bf16_f32 v57, v80, v82
	s_waitcnt lgkmcnt(10)
	v_cvt_pk_bf16_f32 v58, v84, v86
	s_waitcnt lgkmcnt(8)
	v_cvt_pk_bf16_f32 v59, v88, v90
	v_cvt_pk_bf16_f32 v60, v77, v79
	v_cvt_pk_bf16_f32 v61, v81, v83
	v_cvt_pk_bf16_f32 v62, v85, v87
	v_cvt_pk_bf16_f32 v63, v89, v91
	s_waitcnt lgkmcnt(6)
	v_cvt_pk_bf16_f32 v64, v92, v94
	s_waitcnt lgkmcnt(4)
	v_cvt_pk_bf16_f32 v65, v96, v98
	s_waitcnt lgkmcnt(2)
	v_cvt_pk_bf16_f32 v66, v100, v102
	s_waitcnt lgkmcnt(0)
	v_cvt_pk_bf16_f32 v67, v106, v108
	v_cvt_pk_bf16_f32 v68, v93, v95
	v_cvt_pk_bf16_f32 v69, v97, v99
	v_cvt_pk_bf16_f32 v70, v101, v103
	v_cvt_pk_bf16_f32 v71, v107, v109
	global_store_dwordx4 v[104:105], v[40:43], off
	global_store_dwordx4 v[126:127], v[44:47], off
	global_store_dwordx4 v[128:129], v[48:51], off
	global_store_dwordx4 v[130:131], v[52:55], off
	global_store_dwordx4 v[132:133], v[56:59], off
	global_store_dwordx4 v[134:135], v[60:63], off
	global_store_dwordx4 v[136:137], v[64:67], off
	global_store_dwordx4 v[140:141], v[68:71], off
	s_waitcnt lgkmcnt(0)
	s_add_i32 s3, s3, s2
	s_add_i32 s5, s5, s6
	s_cmpk_lt_i32 s3, 0x2b00
	v_add_u32_e32 v7, s4, v7
	s_cbranch_scc1 .LBB0_1653
